# gla_a / gla_c unit start: big tile loads issued after the gate-weight loads with counted waits, so only the gate input is waited on before the gate computation
# baseline (speedup 1.0000x reference)
; #define LAS __attribute__((address_space(3)))
; __device__ __forceinline__ u32x4 mk4(unsigned a, unsigned b, unsigned c, unsigned d) { return (u32x4){a, b, c, d}; }
; __device__ __forceinline__ unsigned pack2(float lo, float hi) { const f32x2_t v = {lo, hi}; const bf16x2_t b = __builtin_convertvector(v, bf16x2_t); return __builtin_bit_cast(unsigned, b); }
; __device__ __forceinline__ float bflo(unsigned w) { return __uint_as_float(w << 16); }
; __device__ __forceinline__ float bfhi(unsigned w) { return __uint_as_float(w & 0xffff0000u); }
; __device__ __forceinline__ void gla_gates(CP P, const bf16_t* PQ, int m0, int h, LAS unsigned char* lds) {
;     ...
;     float off = 0.f;
; #pragma unroll
;     for (int q = 0; q < 4; ++q) { const float tv = tot[(dir * 4 + q) * 64 + d]; off += ((dir == 0) ? (q < tq) : (q > tq)) ? tv : 0.f; }
; #pragma unroll
;     for (int i = 0; i < 16; ++i) G[(dir * 64 + tq * 16 + i) * 64 + d] = c[i] + off;
;     lds_barrier();
; __device__ void gla_c_unit(CP P, int unit, LAS unsigned char* lds) {
;     ...
;     { const unsigned qw[4] = {rq.x, rq.y, rq.z, rq.w}, kw[4] = {rk.x, rk.y, rk.z, rk.w};
;         unsigned oqf[4], okf[4], oqb[4], okb[4]; float cf[8], cb[8];
; #pragma unroll
;         for (int q = 0; q < 2; ++q) { const f32x4 a = *(const LAS f32x4*)(G + t * 64 + d8 + q * 4), bb = *(const LAS f32x4*)(G + (64 + t) * 64 + d8 + q * 4);
; #pragma unroll
;             for (int j = 0; j < 4; ++j) { cf[q * 4 + j] = a[j]; cb[q * 4 + j] = bb[j]; } }
; #pragma unroll
;         for (int i = 0; i < 4; ++i) { const float cf0 = cf[2 * i], cf1 = cf[2 * i + 1], cb0 = cb[2 * i], cb1 = cb[2 * i + 1];
;             const float q0 = bflo(qw[i]) * 0.125f, q1 = bfhi(qw[i]) * 0.125f, k0 = bflo(kw[i]), k1 = bfhi(kw[i]);
;             oqf[i] = pack2(q0 * __expf(cf0), q1 * __expf(cf1)); okf[i] = pack2(k0 * __expf(-cf0), k1 * __expf(-cf1));
;             oqb[i] = pack2(q0 * __expf(cb0), q1 * __expf(cb1)); okb[i] = pack2(k0 * __expf(-cb0), k1 * __expf(-cb1)); }
;         *(LAS u32x4*)(qf + t * 72 + d8) = mk4(oqf[0], oqf[1], oqf[2], oqf[3]); *(LAS u32x4*)(kf + t * 72 + d8) = mk4(okf[0], okf[1], okf[2], okf[3]);
;         *(LAS u32x4*)(qb + t * 72 + d8) = mk4(oqb[0], oqb[1], oqb[2], oqb[3]); *(LAS u32x4*)(kb + t * 72 + d8) = mk4(okb[0], okb[1], okb[2], okb[3]);
.LBB0_171:
	s_or_b64 exec, exec, s[22:23]
	s_waitcnt vmcnt(0)
	ds_read_b32 v55, v55 offset:8960
	v_cmp_ne_u32_e64 s[40:41], 0, v82
	v_add_f32_e32 v46, 0, v46
	s_and_b64 s[40:41], vcc, s[40:41]
	v_cndmask_b32_e64 v46, 0, v46, s[40:41]
	v_cmp_eq_u32_e64 s[40:41], 3, v82
	s_or_b64 s[10:11], vcc, s[40:41]
	v_add_f32_e32 v46, v46, v62
	s_waitcnt lgkmcnt(0)
	v_cndmask_b32_e64 v55, v55, 0, s[10:11]
	v_add_f32_e32 v46, v46, v47
	v_add_f32_e32 v46, v46, v55
	v_lshl_add_u32 v47, v81, 2, 0
	v_lshlrev_b32_e32 v55, 12, v82
	v_lshlrev_b32_e32 v62, 14, v80
	v_add_f32_e32 v54, v54, v46
	v_add3_u32 v47, v47, v55, v62
	v_add_f32_e32 v55, v86, v46
	ds_write2st64_b32 v47, v54, v55 offset0:68 offset1:69
	v_add_f32_e32 v54, v85, v46
	v_add_f32_e32 v55, v61, v46
	ds_write2st64_b32 v47, v54, v55 offset0:70 offset1:71
	v_add_f32_e32 v54, v60, v46
	v_add_f32_e32 v55, v59, v46
	ds_write2st64_b32 v47, v54, v55 offset0:72 offset1:73
	v_add_f32_e32 v54, v58, v46
	v_add_f32_e32 v55, v57, v46
	ds_write2st64_b32 v47, v54, v55 offset0:74 offset1:75
	v_add_f32_e32 v54, v56, v46
	v_add_f32_e32 v53, v53, v46
	v_add_f32_e32 v52, v52, v46
	v_add_f32_e32 v51, v51, v46
	v_add_f32_e32 v50, v50, v46
	v_add_f32_e32 v49, v49, v46
	v_add_f32_e32 v48, v48, v46
	v_add_f32_e32 v45, v45, v46
	v_lshlrev_b32_e32 v70, 3, v79
	ds_write2st64_b32 v47, v54, v53 offset0:76 offset1:77
	ds_write2st64_b32 v47, v52, v51 offset0:78 offset1:79
	ds_write2st64_b32 v47, v50, v49 offset0:80 offset1:81
	ds_write2st64_b32 v47, v48, v45 offset0:82 offset1:83
	v_lshl_add_u32 v45, v41, 8, 0
	s_waitcnt lgkmcnt(0)
	s_barrier
	v_lshl_add_u32 v58, v70, 2, v45
	ds_read_b128 v[46:49], v58 offset:33792
	ds_read_b128 v[50:53], v58 offset:17408
	ds_read_b128 v[54:57], v58 offset:17424
	ds_read_b128 v[58:61], v58 offset:33808
	v_lshlrev_b32_e32 v64, 16, v32
	v_and_b32_e32 v65, 0xffff0000, v32
	s_waitcnt lgkmcnt(2)
	v_mul_f32_e32 v32, 0x3fb8aa3b, v50
	v_exp_f32_e32 v66, v32
	v_mul_f32_e32 v32, 0x3fb8aa3b, v51
	v_exp_f32_e32 v67, v32
	v_mul_f32_e32 v32, 0xbfb8aa3b, v50
	v_lshlrev_b32_e32 v62, 16, v36
	v_and_b32_e32 v63, 0xffff0000, v36
	v_exp_f32_e32 v50, v32
	v_mul_f32_e32 v32, 0xbfb8aa3b, v51
	s_mov_b32 s10, 0x3e000000
	v_exp_f32_e32 v51, v32
	v_mul_f32_e32 v32, 0x3fb8aa3b, v46
	v_pk_mul_f32 v[62:63], v[62:63], s[10:11] op_sel_hi:[1,0]
	v_exp_f32_e32 v68, v32
	v_mul_f32_e32 v32, 0x3fb8aa3b, v47
	v_pk_mul_f32 v[66:67], v[62:63], v[66:67]
	v_mul_f32_e32 v36, 0xbfb8aa3b, v46
	v_exp_f32_e32 v69, v32
	v_cvt_pk_bf16_f32 v32, v66, v67
	v_exp_f32_e32 v66, v36
	v_mul_f32_e32 v36, 0xbfb8aa3b, v47
	v_exp_f32_e32 v67, v36
	v_pk_mul_f32 v[46:47], v[50:51], v[64:65]
	v_pk_mul_f32 v[62:63], v[62:63], v[68:69]
	v_cvt_pk_bf16_f32 v46, v46, v47
	v_pk_mul_f32 v[50:51], v[66:67], v[64:65]
	v_lshlrev_b32_e32 v64, 16, v33
	v_and_b32_e32 v65, 0xffff0000, v33
	v_mul_f32_e32 v33, 0x3fb8aa3b, v52
	v_exp_f32_e32 v66, v33
	v_mul_f32_e32 v33, 0x3fb8aa3b, v53
	v_exp_f32_e32 v67, v33
	v_mul_f32_e32 v33, 0xbfb8aa3b, v52
	v_exp_f32_e32 v52, v33
	v_mul_f32_e32 v33, 0xbfb8aa3b, v53
	v_exp_f32_e32 v53, v33
	v_mul_f32_e32 v33, 0x3fb8aa3b, v48
	v_exp_f32_e32 v68, v33
	v_mul_f32_e32 v33, 0x3fb8aa3b, v49
	v_exp_f32_e32 v69, v33
	v_cvt_pk_bf16_f32 v36, v62, v63
	v_lshlrev_b32_e32 v62, 16, v37
	v_and_b32_e32 v63, 0xffff0000, v37
	v_mul_f32_e32 v37, 0xbfb8aa3b, v48
	v_pk_mul_f32 v[62:63], v[62:63], s[10:11] op_sel_hi:[1,0]
	v_exp_f32_e32 v48, v37
	v_mul_f32_e32 v37, 0xbfb8aa3b, v49
	v_pk_mul_f32 v[52:53], v[52:53], v[64:65]
	v_pk_mul_f32 v[66:67], v[62:63], v[66:67]
	v_pk_mul_f32 v[62:63], v[62:63], v[68:69]
	v_exp_f32_e32 v49, v37
	v_cvt_pk_bf16_f32 v47, v52, v53
	v_lshlrev_b32_e32 v52, 16, v34
	v_and_b32_e32 v53, 0xffff0000, v34
	s_waitcnt lgkmcnt(1)
	v_mul_f32_e32 v34, 0x3fb8aa3b, v54
	v_cvt_pk_bf16_f32 v37, v62, v63
	v_exp_f32_e32 v62, v34
	v_mul_f32_e32 v34, 0x3fb8aa3b, v55
	v_exp_f32_e32 v63, v34
	v_mul_f32_e32 v34, 0xbfb8aa3b, v54
	v_exp_f32_e32 v54, v34
	v_mul_f32_e32 v34, 0xbfb8aa3b, v55
	v_pk_mul_f32 v[48:49], v[48:49], v[64:65]
	v_exp_f32_e32 v55, v34
	s_waitcnt lgkmcnt(0)
	v_mul_f32_e32 v34, 0x3fb8aa3b, v58
	v_cvt_pk_bf16_f32 v50, v50, v51
	v_cvt_pk_bf16_f32 v51, v48, v49
	v_lshlrev_b32_e32 v48, 16, v38
	v_and_b32_e32 v49, 0xffff0000, v38
	v_exp_f32_e32 v64, v34
	v_mul_f32_e32 v34, 0x3fb8aa3b, v59
	v_mul_f32_e32 v38, 0xbfb8aa3b, v58
	v_exp_f32_e32 v65, v34
	v_exp_f32_e32 v58, v38
	v_mul_f32_e32 v38, 0xbfb8aa3b, v59
	v_exp_f32_e32 v59, v38
	v_pk_mul_f32 v[48:49], v[48:49], s[10:11] op_sel_hi:[1,0]
	v_cvt_pk_bf16_f32 v33, v66, v67
	v_pk_mul_f32 v[62:63], v[48:49], v[62:63]
	v_pk_mul_f32 v[48:49], v[48:49], v[64:65]
	v_cvt_pk_bf16_f32 v34, v62, v63
	v_cvt_pk_bf16_f32 v38, v48, v49
	v_pk_mul_f32 v[48:49], v[54:55], v[52:53]
	v_pk_mul_f32 v[52:53], v[58:59], v[52:53]
	v_lshlrev_b32_e32 v58, 16, v35
	v_and_b32_e32 v59, 0xffff0000, v35
	v_mul_f32_e32 v35, 0x3fb8aa3b, v56
	v_exp_f32_e32 v62, v35
	v_mul_f32_e32 v35, 0x3fb8aa3b, v57
	v_exp_f32_e32 v63, v35
	v_mul_f32_e32 v35, 0xbfb8aa3b, v56
	v_exp_f32_e32 v56, v35
	v_mul_f32_e32 v35, 0xbfb8aa3b, v57
	v_exp_f32_e32 v57, v35
	v_mul_f32_e32 v35, 0x3fb8aa3b, v60
	v_exp_f32_e32 v64, v35
	v_mul_f32_e32 v35, 0x3fb8aa3b, v61
	v_lshlrev_b32_e32 v54, 16, v39
	v_and_b32_e32 v55, 0xffff0000, v39
	v_exp_f32_e32 v65, v35
	v_mul_f32_e32 v39, 0xbfb8aa3b, v60
	v_exp_f32_e32 v60, v39
	v_mul_f32_e32 v39, 0xbfb8aa3b, v61
	v_exp_f32_e32 v61, v39
	v_pk_mul_f32 v[54:55], v[54:55], s[10:11] op_sel_hi:[1,0]
	v_cvt_pk_bf16_f32 v48, v48, v49
	v_pk_mul_f32 v[62:63], v[54:55], v[62:63]
	v_pk_mul_f32 v[54:55], v[54:55], v[64:65]
	s_movk_i32 s10, 0xff90
	v_cvt_pk_bf16_f32 v39, v54, v55
	v_pk_mul_f32 v[54:55], v[56:57], v[58:59]
; #define LAS __attribute__((address_space(3)))
; __device__ __forceinline__ u32x4 mk4(unsigned a, unsigned b, unsigned c, unsigned d) { return (u32x4){a, b, c, d}; }
; __device__ __forceinline__ u32x2 mk2(unsigned a, unsigned b) { return (u32x2){a, b}; }
; __device__ __forceinline__ unsigned pack2(float lo, float hi) { const f32x2_t v = {lo, hi}; const bf16x2_t b = __builtin_convertvector(v, bf16x2_t); return __builtin_bit_cast(unsigned, b); }
; __device__ __forceinline__ void lds_barrier() { asm volatile("s_waitcnt lgkmcnt(0)" ::: "memory"); __builtin_amdgcn_s_barrier(); asm volatile("" ::: "memory"); }
; __device__ void gla_c_unit(CP P, int unit, LAS unsigned char* lds) {
;     ...
;         *(LAS u32x4*)(qf + t * 72 + d8) = mk4(oqf[0], oqf[1], oqf[2], oqf[3]); *(LAS u32x4*)(kf + t * 72 + d8) = mk4(okf[0], okf[1], okf[2], okf[3]);
;         *(LAS u32x4*)(qb + t * 72 + d8) = mk4(oqb[0], oqb[1], oqb[2], oqb[3]); *(LAS u32x4*)(kb + t * 72 + d8) = mk4(okb[0], okb[1], okb[2], okb[3]);
;         *(LAS u32x4*)(Vs + t * 136 + v16) = mk4(vr0.x, vr0.y, vr0.z, vr0.w); *(LAS u32x4*)(Vs + t * 136 + v16 + 8) = mk4(vr1.x, vr1.y, vr1.z, vr1.w); }
; #pragma unroll
;     for (int i = 0; i < 4; ++i) { const int idx = tid + i * NTHR, v8 = (idx & 15) * 8, d = (idx >> 4) & 63, dir = idx >> 10;
;         *(LAS u32x4*)(Ss + (dir * 64 + d) * 136 + v8) = mk4(sr[i].x, sr[i].y, sr[i].z, sr[i].w); }
;     lds_barrier();
; #pragma unroll
;     for (int tl = 0; tl < 2; ++tl) { const int tile = wid * 2 + tl, mi = tile >> 2, ni = tile & 3; f32x4 pf = (f32x4){0.f, 0.f, 0.f, 0.f}, pb = pf;
;         pf = mma16(qf + mi * 16 * 72, 72, kf + ni * 16 * 72, 72, 64, pf, lane); pb = mma16(qb + mi * 16 * 72, 72, kb + ni * 16 * 72, 72, 64, pb, lane);
;         const int i = mi * 16 + (lane & 15), j0 = ni * 16 + 4 * (lane >> 4); float pv[4];
; #pragma unroll
;         for (int jj = 0; jj < 4; ++jj) pv[jj] = (j0 + jj <= i) ? pf[jj] : pb[jj];
;         *(LAS u32x2*)(Ps + i * 72 + j0) = mk2(pack2(pv[0], pv[1]), pack2(pv[2], pv[3])); }
;     lds_barrier();
	v_cvt_pk_bf16_f32 v52, v52, v53
	v_cvt_pk_bf16_f32 v49, v54, v55
	v_pk_mul_f32 v[54:55], v[60:61], v[58:59]
	v_cvt_pk_bf16_f32 v35, v62, v63
	v_cvt_pk_bf16_f32 v53, v54, v55
	v_mul_lo_u32 v54, v41, s10
	v_lshlrev_b32_e32 v55, 1, v70
	v_add3_u32 v45, v45, v54, v55
	s_movk_i32 s12, 0x90
	ds_write_b128 v45, v[32:35] offset:51200
	ds_write_b128 v45, v[46:49] offset:60416
	v_mul_lo_u32 v32, v41, s12
	v_readlane_b32 s13, v254, 32
	v_readlane_b32 s18, v254, 33
	s_movk_i32 s19, 0x110
	v_add3_u32 v33, s13, v32, v55
	v_add3_u32 v32, s18, v32, v55
	ds_write_b128 v33, v[36:39]
	ds_write_b128 v32, v[50:53]
	v_mul_lo_u32 v33, v41, s19
	v_lshlrev_b32_e32 v32, 1, v42
	v_readlane_b32 s21, v254, 34
	v_readlane_b32 s20, v254, 36
	v_ashrrev_i32_e32 v44, 6, v74
	v_add3_u32 v33, s21, v33, v32
	ds_write_b128 v33, v[12:15]
	ds_write_b128 v33, v[8:11] offset:16
	v_lshl_add_u32 v8, v75, 1, s20
	v_lshrrev_b32_e32 v9, 4, v74
	v_mad_u64_u32 v[10:11], s[10:11], v9, s19, v[8:9]
	v_lshrrev_b32_e32 v9, 4, v76
	ds_write_b128 v10, v[16:19]
	v_mad_u64_u32 v[10:11], s[10:11], v9, s19, v[8:9]
	v_bfe_u32 v12, v74, 4, 6
	v_lshrrev_b32_e32 v9, 4, v77
	s_mov_b32 s10, 0xfffffc0
	v_and_or_b32 v9, v9, s10, v12
	ds_write_b128 v10, v[20:23]
	v_mad_u64_u32 v[10:11], s[10:11], v9, s19, v[8:9]
	v_lshrrev_b32_e32 v9, 4, v78
	v_mad_u64_u32 v[8:9], s[10:11], v9, s19, v[8:9]
	ds_write_b128 v10, v[24:27]
	ds_write_b128 v8, v[28:31]
	v_lshlrev_b32_e32 v8, 1, v44
	v_and_b32_e32 v33, 2, v8
	v_and_b32_e32 v8, -16, v41
	v_and_b32_e32 v34, 15, v74
	v_mul_lo_u32 v12, v8, s12
	v_mul_u32_u24_e32 v8, 0x48, v34
	v_lshlrev_b32_e32 v28, 1, v8
	v_lshrrev_b32_e32 v8, 1, v74
	v_and_b32_e32 v35, 24, v8
	v_lshlrev_b32_e32 v36, 1, v35
	v_mul_u32_u24_e32 v8, 0x480, v33
	v_add3_u32 v13, 0, v28, v36
	v_lshlrev_b32_e32 v24, 1, v8
	s_waitcnt lgkmcnt(0)
	s_barrier
	v_add_u32_e32 v37, v13, v24
	ds_read_b128 v[8:11], v37 offset:60416
	v_add_u32_e32 v25, s18, v28
	v_add_u32_e32 v38, v13, v12
	v_add3_u32 v39, v25, v36, v24
	v_add_u32_e32 v29, s13, v12
	ds_read_b128 v[12:15], v38 offset:51200
	ds_read_b128 v[16:19], v37 offset:60480
	ds_read_b128 v[20:23], v38 offset:51264
	ds_read_b128 v[24:27], v39
	s_waitcnt lgkmcnt(3)
	v_mfma_f32_16x16x32_bf16 v[8:11], v[8:11], v[12:15], 0
	v_add3_u32 v45, v29, v28, v36
	ds_read_b128 v[12:15], v45
	ds_read_b128 v[28:31], v39 offset:64
	v_lshrrev_b32_e32 v47, 2, v74
	s_waitcnt lgkmcnt(3)
	v_mfma_f32_16x16x32_bf16 v[8:11], v[16:19], v[20:23], v[8:11]
	ds_read_b128 v[16:19], v45 offset:64
	v_bfi_b32 v46, -16, v41, v74
	v_mul_lo_u32 v20, v46, s12
	s_waitcnt lgkmcnt(2)
	v_mfma_f32_16x16x32_bf16 v[12:15], v[24:27], v[12:15], 0
	v_and_b32_e32 v24, 12, v47
	v_add_u32_e32 v25, 0, v20
	s_add_i32 s10, 0, 0x1e000
	s_waitcnt lgkmcnt(0)
	v_mfma_f32_16x16x32_bf16 v[12:15], v[28:31], v[16:19], v[12:15]
	v_lshl_or_b32 v30, v33, 4, v24
	v_cmp_gt_i32_e32 vcc, v30, v46
	v_lshlrev_b32_e32 v42, 2, v42
	s_lshl_b32 s12, s66, 2
	s_nop 3
	v_cndmask_b32_e32 v8, v8, v12, vcc
	v_cmp_lt_i32_e32 vcc, v30, v46
	v_or_b32_e32 v12, 2, v30
	s_nop 0
	v_cndmask_b32_e32 v9, v13, v9, vcc
	v_cmp_gt_i32_e32 vcc, v12, v46
	v_or_b32_e32 v12, 3, v30
	v_cvt_pk_bf16_f32 v8, v8, v9
	v_cndmask_b32_e32 v10, v10, v14, vcc
	v_cmp_gt_i32_e32 vcc, v12, v46
	s_nop 1
	v_cndmask_b32_e32 v11, v11, v15, vcc
	v_cvt_pk_bf16_f32 v9, v10, v11
	v_lshl_add_u32 v10, v30, 1, v25
	ds_write_b64 v10, v[8:9]
	ds_read_b128 v[8:11], v37 offset:62720
	ds_read_b128 v[12:15], v38 offset:51200
	ds_read_b128 v[16:19], v37 offset:62784
	s_waitcnt lgkmcnt(1)
	v_mfma_f32_16x16x32_bf16 v[8:11], v[8:11], v[12:15], 0
	ds_read_b128 v[12:15], v38 offset:51264
	ds_read_b128 v[20:23], v39 offset:2304
	ds_read_b128 v[26:29], v45
	s_waitcnt lgkmcnt(2)
	v_mfma_f32_16x16x32_bf16 v[8:11], v[16:19], v[12:15], v[8:11]
	ds_read_b128 v[12:15], v39 offset:2368
	s_waitcnt lgkmcnt(1)
	v_mfma_f32_16x16x32_bf16 v[16:19], v[20:23], v[26:29], 0
	ds_read_b128 v[20:23], v45 offset:64
	v_and_b32_e32 v39, 24, v43
	s_waitcnt lgkmcnt(0)
	v_mfma_f32_16x16x32_bf16 v[12:15], v[12:15], v[20:23], v[16:19]
	s_nop 3
	v_or_b32_e32 v16, 16, v30
	v_cmp_gt_i32_e32 vcc, v16, v46
	s_nop 1
	v_cndmask_b32_e32 v8, v8, v12, vcc
	v_cmp_lt_i32_e32 vcc, v16, v46
	v_or_b32_e32 v12, 18, v30
	s_nop 0
	v_cndmask_b32_e32 v9, v13, v9, vcc
	v_cmp_gt_i32_e32 vcc, v12, v46
	v_or_b32_e32 v12, 19, v30
	v_cvt_pk_bf16_f32 v8, v8, v9
	v_cndmask_b32_e32 v10, v10, v14, vcc
	v_cmp_gt_i32_e32 vcc, v12, v46
	s_nop 1
	v_cndmask_b32_e32 v11, v11, v15, vcc
	v_cvt_pk_bf16_f32 v9, v10, v11
	v_lshl_add_u32 v10, v16, 1, v25
	ds_write_b64 v10, v[8:9]
	v_lshlrev_b32_e32 v8, 4, v44
	v_and_or_b32 v26, v8, 48, v34
	v_mul_u32_u24_e32 v8, 0x48, v26
	v_lshlrev_b32_e32 v27, 1, v8
	v_and_or_b32 v8, v47, 3, v35
	v_mul_u32_u24_e32 v8, 0x88, v8
	v_and_b32_e32 v25, -4, v44
	v_lshlrev_b32_e32 v38, 1, v8
	v_add3_u32 v43, s21, v38, v39
	v_lshlrev_b32_e32 v54, 5, v25
	s_waitcnt lgkmcnt(0)
	s_barrier
; #define LAS __attribute__((address_space(3)))
; __device__ void gla_c_unit(CP P, int unit, LAS unsigned char* lds) {
;     ...
;     { const int mi = wid & 3, nb = (wid >> 2) * 4; LAS float* ost = G; f32x4 acc[4];
; #pragma unroll
;         for (int nt = 0; nt < 4; ++nt) acc[nt] = (f32x4){0.f, 0.f, 0.f, 0.f};
; #pragma unroll
;         for (int ks = 0; ks < 2; ++ks) {
;             const bf16x8 ap = *(const LAS bf16x8*)(Ps + (mi * 16 + (lane & 15)) * 72 + ks * 32 + (lane >> 4) * 8);
;             const bf16x8 af = *(const LAS bf16x8*)(qf + (mi * 16 + (lane & 15)) * 72 + ks * 32 + (lane >> 4) * 8);
;             const bf16x8 ab = *(const LAS bf16x8*)(qb + (mi * 16 + (lane & 15)) * 72 + ks * 32 + (lane >> 4) * 8);
; #pragma unroll
;             for (int nt = 0; nt < 4; ++nt) { const int ni = nb + nt;
;                 acc[nt] = __builtin_amdgcn_mfma_f32_16x16x32_bf16(frag_tr(Vs + ks * 32 * 136 + ni * 16, 136, lane), ap, acc[nt], 0, 0, 0);
;                 acc[nt] = __builtin_amdgcn_mfma_f32_16x16x32_bf16(frag_tr(Ss + ks * 32 * 136 + ni * 16, 136, lane), af, acc[nt], 0, 0, 0);
;                 acc[nt] = __builtin_amdgcn_mfma_f32_16x16x32_bf16(frag_tr(Ss + (64 + ks * 32) * 136 + ni * 16, 136, lane), ab, acc[nt], 0, 0, 0); } }
; #pragma unroll
;         for (int nt = 0; nt < 4; ++nt) *(LAS f32x4*)(ost + (mi * 16 + (lane & 15)) * 132 + (nb + nt) * 16 + 4 * (lane >> 4)) = acc[nt]; }
	v_add_u32_e32 v56, v43, v54
	v_add3_u32 v33, 0, v27, v36
	ds_read_b64_tr_b16 v[10:11], v56 offset:1088
	ds_read_b64_tr_b16 v[8:9], v56
	ds_read_b128 v[12:15], v33
	ds_read_b128 v[16:19], v33 offset:51200
	v_add3_u32 v55, s20, v38, v39
	v_add_u32_e32 v57, v55, v54
	ds_read_b64_tr_b16 v[22:23], v57 offset:1088
	ds_read_b64_tr_b16 v[20:21], v57
	s_waitcnt lgkmcnt(3)
	v_mfma_f32_16x16x32_bf16 v[8:11], v[8:11], v[12:15], 0
	v_add3_u32 v58, s10, v38, v39
	v_add_u32_e32 v45, v58, v54
	ds_read_b64_tr_b16 v[30:31], v45 offset:1088
	ds_read_b64_tr_b16 v[28:29], v45
	v_add3_u32 v27, s13, v27, v36
	s_waitcnt lgkmcnt(2)
	v_mfma_f32_16x16x32_bf16 v[8:11], v[20:23], v[16:19], v[8:11]
	ds_read_b128 v[34:37], v27
	ds_read_b64_tr_b16 v[20:21], v56 offset:32
	v_readlane_b32 s10, v254, 37
	s_waitcnt lgkmcnt(1)
	v_mfma_f32_16x16x32_bf16 v[28:31], v[28:31], v[34:37], v[8:11]
	ds_read_b64_tr_b16 v[22:23], v56 offset:1120
	s_nop 1
	ds_read_b64_tr_b16 v[8:9], v57 offset:32
	ds_read_b64_tr_b16 v[10:11], v57 offset:1120
	ds_read_b64_tr_b16 v[46:47], v45 offset:32
	ds_read_b64_tr_b16 v[48:49], v45 offset:1120
	s_waitcnt lgkmcnt(4)
	v_mfma_f32_16x16x32_bf16 v[20:23], v[20:23], v[12:15], 0
	s_waitcnt lgkmcnt(2)
	v_mfma_f32_16x16x32_bf16 v[8:11], v[8:11], v[16:19], v[20:23]
	s_waitcnt lgkmcnt(0)
	v_mfma_f32_16x16x32_bf16 v[20:23], v[46:49], v[34:37], v[8:11]
	s_nop 5
	ds_read_b64_tr_b16 v[8:9], v56 offset:64
	ds_read_b64_tr_b16 v[10:11], v56 offset:1152
	ds_read_b64_tr_b16 v[46:47], v57 offset:64
	ds_read_b64_tr_b16 v[48:49], v57 offset:1152
	ds_read_b64_tr_b16 v[50:51], v45 offset:64
	ds_read_b64_tr_b16 v[52:53], v45 offset:1152
	v_mov_b32_e32 v45, 0x60
	s_waitcnt lgkmcnt(4)
	v_mfma_f32_16x16x32_bf16 v[8:11], v[8:11], v[12:15], 0
	v_lshl_or_b32 v59, v44, 5, v45
	v_add_u32_e32 v43, v43, v59
	v_add_u32_e32 v60, v55, v59
	s_waitcnt lgkmcnt(2)
	v_mfma_f32_16x16x32_bf16 v[8:11], v[46:49], v[16:19], v[8:11]
	ds_read_b64_tr_b16 v[44:45], v43
	ds_read_b64_tr_b16 v[46:47], v43 offset:1088
	s_waitcnt lgkmcnt(2)
	v_mfma_f32_16x16x32_bf16 v[48:51], v[50:53], v[34:37], v[8:11]
	s_nop 3
	ds_read_b64_tr_b16 v[8:9], v60
	ds_read_b64_tr_b16 v[10:11], v60 offset:1088
	s_waitcnt lgkmcnt(2)
	v_mfma_f32_16x16x32_bf16 v[12:15], v[44:47], v[12:15], 0
	v_add_u32_e32 v46, v58, v59
	ds_read_b64_tr_b16 v[44:45], v46
	ds_read_b64_tr_b16 v[46:47], v46 offset:1088
	s_waitcnt lgkmcnt(2)
	v_mfma_f32_16x16x32_bf16 v[8:11], v[8:11], v[16:19], v[12:15]
	s_nop 2
	ds_read_b64_tr_b16 v[12:13], v56 offset:8704
	ds_read_b64_tr_b16 v[14:15], v56 offset:9792
	s_waitcnt lgkmcnt(2)
	v_mfma_f32_16x16x32_bf16 v[8:11], v[44:47], v[34:37], v[8:11]
	ds_read_b128 v[34:37], v33 offset:64
	ds_read_b64_tr_b16 v[16:17], v57 offset:8704
	ds_read_b64_tr_b16 v[18:19], v57 offset:9792
	ds_read_b128 v[44:47], v33 offset:51264
	v_add3_u32 v33, s10, v38, v39
	v_add_u32_e32 v38, v33, v54
	s_waitcnt lgkmcnt(3)
	v_mfma_f32_16x16x32_bf16 v[12:15], v[12:15], v[34:37], v[28:31]
	s_nop 2
	ds_read_b64_tr_b16 v[30:31], v38 offset:1088
	ds_read_b64_tr_b16 v[28:29], v38
	s_movk_i32 s10, 0x210
	v_and_b32_e32 v39, 0xffff0000, v4
	s_waitcnt lgkmcnt(2)
	v_mfma_f32_16x16x32_bf16 v[12:15], v[16:19], v[44:47], v[12:15]
	ds_read_b128 v[16:19], v27 offset:64
	v_add_u32_e32 v27, v33, v59
	v_mov_b32_e32 v33, v184
	s_waitcnt lgkmcnt(0)
	v_mfma_f32_16x16x32_bf16 v[12:15], v[28:31], v[16:19], v[12:15]
	ds_read_b64_tr_b16 v[28:29], v56 offset:8736
	ds_read_b64_tr_b16 v[30:31], v56 offset:9824
	s_waitcnt lgkmcnt(0)
	v_mfma_f32_16x16x32_bf16 v[20:23], v[28:31], v[34:37], v[20:23]
	ds_read_b64_tr_b16 v[28:29], v57 offset:8736
	ds_read_b64_tr_b16 v[30:31], v57 offset:9824
	ds_read_b64_tr_b16 v[52:53], v38 offset:32
	ds_read_b64_tr_b16 v[54:55], v38 offset:1120
	s_waitcnt lgkmcnt(2)
	v_mfma_f32_16x16x32_bf16 v[20:23], v[28:31], v[44:47], v[20:23]
	ds_read_b64_tr_b16 v[28:29], v56 offset:8768
	ds_read_b64_tr_b16 v[30:31], v56 offset:9856
	s_waitcnt lgkmcnt(0)
	v_mfma_f32_16x16x32_bf16 v[28:31], v[28:31], v[34:37], v[48:51]
	s_nop 2
	ds_read_b64_tr_b16 v[48:49], v57 offset:8768
	ds_read_b64_tr_b16 v[50:51], v57 offset:9856
	s_waitcnt lgkmcnt(0)
	v_mfma_f32_16x16x32_bf16 v[28:31], v[48:51], v[44:47], v[28:31]
	ds_read_b64_tr_b16 v[48:49], v38 offset:64
	ds_read_b64_tr_b16 v[50:51], v38 offset:1152
	v_lshlrev_b32_e32 v38, 16, v4
	v_mul_f32_e32 v4, 0xbfb8aa3b, v38
	s_waitcnt lgkmcnt(0)
	v_mfma_f32_16x16x32_bf16 v[28:31], v[48:51], v[16:19], v[28:31]
	ds_read_b64_tr_b16 v[48:49], v43 offset:8704
	ds_read_b64_tr_b16 v[50:51], v43 offset:9792
	v_exp_f32_e32 v4, v4
	s_waitcnt lgkmcnt(0)
	v_mfma_f32_16x16x32_bf16 v[8:11], v[48:51], v[34:37], v[8:11]
	ds_read_b64_tr_b16 v[34:35], v60 offset:8704
	ds_read_b64_tr_b16 v[36:37], v60 offset:9792
	v_add_f32_e32 v4, 1.0, v4
	s_waitcnt lgkmcnt(0)
	v_mfma_f32_16x16x32_bf16 v[8:11], v[34:37], v[44:47], v[8:11]
	ds_read_b64_tr_b16 v[34:35], v27
	ds_read_b64_tr_b16 v[36:37], v27 offset:1088
	v_mfma_f32_16x16x32_bf16 v[20:23], v[52:55], v[16:19], v[20:23]
	s_waitcnt lgkmcnt(0)
	v_mfma_f32_16x16x32_bf16 v[8:11], v[34:37], v[16:19], v[8:11]
	v_mul_u32_u24_e32 v16, 0x210, v26
	v_lshlrev_b32_e32 v17, 2, v24
	v_add3_u32 v16, 0, v16, v17
	v_lshl_add_u32 v17, v25, 6, v16
	ds_write_b128 v17, v[12:15] offset:17408
	s_nop 0
	ds_write_b128 v17, v[20:23] offset:17472
	ds_write_b128 v17, v[28:31] offset:17536
	v_and_b32_e32 v12, 0xffffff00, v74
	v_add_u32_e32 v12, v16, v12
	ds_write_b128 v12, v[8:11] offset:17600
	v_mul_lo_u32 v8, v41, s10
	s_waitcnt lgkmcnt(0)
	s_barrier
; #define LAS __attribute__((address_space(3)))
; __device__ __forceinline__ unsigned pack2(float lo, float hi) { const f32x2_t v = {lo, hi}; const bf16x2_t b = __builtin_convertvector(v, bf16x2_t); return __builtin_bit_cast(unsigned, b); }
; __device__ __forceinline__ float bflo(unsigned w) { return __uint_as_float(w << 16); }
; __device__ __forceinline__ float bfhi(unsigned w) { return __uint_as_float(w & 0xffff0000u); }
; __device__ __forceinline__ float silu_f(float x) { return x * fast_sigmoid(x); }
; __device__ __forceinline__ void lds_barrier() { asm volatile("s_waitcnt lgkmcnt(0)" ::: "memory"); __builtin_amdgcn_s_barrier(); asm volatile("" ::: "memory"); }
; __device__ void gla_c_unit(CP P, int unit, LAS unsigned char* lds) {
;     ...
;     { LAS float* ost = G; float o[16]; float ss = 0.f;
; #pragma unroll
;         for (int i = 0; i < 4; ++i) { const f32x4 v = *(const LAS f32x4*)(ost + t * 132 + v16 + i * 4); o[4 * i] = v[0]; o[4 * i + 1] = v[1]; o[4 * i + 2] = v[2]; o[4 * i + 3] = v[3]; ss += v[0] * v[0] + v[1] * v[1] + v[2] * v[2] + v[3] * v[3]; }
;         ss += __shfl_xor(ss, 1); ss += __shfl_xor(ss, 2); ss += __shfl_xor(ss, 4);
;         const float rstd = rsqrtf(ss * (1.0f / 128.0f) + 1e-6f);
;         const float* gn = P->in[20] + h * 128 + v16;
;         bf16_t* op = MIX + (size_t)(m0 + t) * 1024 + 512 + h * 128 + v16;
; #pragma unroll
;         for (int hh = 0; hh < 2; ++hh) { const uint4 raw = hh ? ogr1 : ogr0; const unsigned rw[4] = {raw.x, raw.y, raw.z, raw.w}; unsigned ow[4];
; #pragma unroll
;             for (int i = 0; i < 4; ++i) { const int e = hh * 8 + 2 * i; const float g0 = bflo(rw[i]), g1 = bfhi(rw[i]);
;                 ow[i] = pack2(o[e] * rstd * gn[e] * silu_f(g0), o[e + 1] * rstd * gn[e + 1] * silu_f(g1)); }
;             *(uint4*)(op + hh * 8) = make_uint4(ow[0], ow[1], ow[2], ow[3]); } }
;     lds_barrier();
	v_add3_u32 v8, 0, v8, v42
	ds_read_b128 v[20:23], v8 offset:17408
	ds_read_b128 v[16:19], v8 offset:17424
	ds_read_b128 v[12:15], v8 offset:17440
	ds_read_b128 v[8:11], v8 offset:17456
	s_load_dwordx2 s[10:11], s[0:1], 0xa0
	s_waitcnt lgkmcnt(0)
	v_mov_b32_e32 v26, v21
	v_mov_b32_e32 v27, v17
	v_mov_b32_e32 v24, v20
	v_mov_b32_e32 v25, v16
	s_add_u32 s20, s10, s12
	v_pk_mul_f32 v[26:27], v[26:27], v[26:27]
	s_addc_u32 s21, s11, 0
	v_pk_fma_f32 v[24:25], v[24:25], v[24:25], v[26:27]
	global_load_dwordx4 v[26:29], v42, s[20:21]
	v_mov_b32_e32 v30, v22
	v_mov_b32_e32 v31, v18
	v_pk_fma_f32 v[24:25], v[30:31], v[30:31], v[24:25]
	v_mov_b32_e32 v30, v23
	v_mov_b32_e32 v31, v19
	v_mov_b32_e32 v34, v13
	v_mov_b32_e32 v35, v9
	v_pk_fma_f32 v[24:25], v[30:31], v[30:31], v[24:25]
	v_mov_b32_e32 v30, v12
	v_mov_b32_e32 v31, v8
	v_pk_mul_f32 v[34:35], v[34:35], v[34:35]
	v_add_f32_e32 v24, v24, v25
	v_pk_fma_f32 v[30:31], v[30:31], v[30:31], v[34:35]
	v_mov_b32_e32 v34, v14
	v_mov_b32_e32 v35, v10
	v_pk_fma_f32 v[30:31], v[34:35], v[34:35], v[30:31]
	v_mov_b32_e32 v34, v15
	v_mov_b32_e32 v35, v11
	v_pk_fma_f32 v[30:31], v[34:35], v[34:35], v[30:31]
	global_load_dwordx4 v[34:37], v42, s[20:21] offset:16
	v_add_f32_e32 v24, v24, v30
	v_and_b32_e32 v30, 64, v226
	v_xor_b32_e32 v25, 1, v226
	v_add_u32_e32 v30, 64, v30
	v_cmp_lt_i32_e32 vcc, v25, v30
	v_add_f32_e32 v24, v24, v31
	v_ashrrev_i32_e32 v41, 31, v40
	v_cndmask_b32_e32 v25, v226, v25, vcc
	v_lshlrev_b32_e32 v25, 2, v25
	ds_bpermute_b32 v25, v25, v24
	s_lshl_b32 s66, s66, 1
	s_mov_b32 s10, 0x32200000
	s_add_i32 s17, s17, s16
	s_cmpk_gt_i32 s17, 0xfff
	s_waitcnt lgkmcnt(0)
	v_add_f32_e32 v24, v24, v25
	v_xor_b32_e32 v25, 2, v226
	v_cmp_lt_i32_e32 vcc, v25, v30
	s_nop 1
	v_cndmask_b32_e32 v25, v226, v25, vcc
	v_lshlrev_b32_e32 v25, 2, v25
	ds_bpermute_b32 v25, v25, v24
	s_waitcnt lgkmcnt(0)
	v_add_f32_e32 v24, v24, v25
	v_xor_b32_e32 v25, 4, v226
	v_cmp_lt_i32_e32 vcc, v25, v30
	v_mov_b32_e32 v30, 0x358637bd
	s_nop 0
	v_cndmask_b32_e32 v25, v226, v25, vcc
	v_lshlrev_b32_e32 v25, 2, v25
	ds_bpermute_b32 v25, v25, v24
	s_waitcnt lgkmcnt(0)
	v_add_f32_e32 v24, v24, v25
	v_fmamk_f32 v24, v24, 0x3c000000, v30
	v_cmp_gt_f32_e32 vcc, s80, v24
	v_mul_f32_e32 v25, 0x4b800000, v24
	v_lshlrev_b64 v[30:31], 11, v[40:41]
	v_cndmask_b32_e32 v24, v24, v25, vcc
	v_rsq_f32_e32 v24, v24
	v_lshl_add_u64 v[30:31], s[94:95], 0, v[30:31]
	v_rcp_f32_e32 v40, v4
	v_lshl_add_u64 v[30:31], v[30:31], 0, s[66:67]
	v_mul_f32_e32 v25, 0x45800000, v24
	v_cndmask_b32_e32 v24, v24, v25, vcc
	v_mul_f32_e32 v25, 0xbfb8aa3b, v39
	v_exp_f32_e32 v25, v25
	v_lshl_add_u64 v[30:31], v[30:31], 0, v[32:33]
	v_lshlrev_b32_e32 v32, 16, v5
	v_and_b32_e32 v33, 0xffff0000, v5
	v_add_f32_e32 v4, 1.0, v25
	v_rcp_f32_e32 v41, v4
	v_mul_f32_e32 v4, 0xbfb8aa3b, v32
	v_pk_mul_f32 v[20:21], v[20:21], v[24:25] op_sel_hi:[1,0]
	v_exp_f32_e32 v25, v4
	v_mul_f32_e32 v4, 0xbfb8aa3b, v33
	s_waitcnt vmcnt(1)
	v_pk_mul_f32 v[20:21], v[26:27], v[20:21]
	v_pk_mul_f32 v[26:27], v[40:41], v[38:39]
	v_exp_f32_e32 v38, v4
	v_pk_mul_f32 v[4:5], v[26:27], v[20:21]
	v_lshlrev_b32_e32 v26, 16, v6
	v_add_f32_e32 v20, 1.0, v25
	v_add_f32_e32 v21, 1.0, v38
	v_cvt_pk_bf16_f32 v4, v4, v5
	v_and_b32_e32 v27, 0xffff0000, v6
	v_mul_f32_e32 v5, 0xbfb8aa3b, v26
	v_rcp_f32_e32 v20, v20
	v_rcp_f32_e32 v21, v21
	v_exp_f32_e32 v5, v5
	v_mul_f32_e32 v6, 0xbfb8aa3b, v27
	v_exp_f32_e32 v6, v6
	v_pk_mul_f32 v[22:23], v[22:23], v[24:25] op_sel_hi:[1,0]
	v_pk_mul_f32 v[20:21], v[20:21], v[32:33]
	v_pk_mul_f32 v[22:23], v[28:29], v[22:23]
	v_add_f32_e32 v5, 1.0, v5
	v_pk_mul_f32 v[20:21], v[20:21], v[22:23]
	v_rcp_f32_e32 v22, v5
	v_add_f32_e32 v5, 1.0, v6
	v_rcp_f32_e32 v23, v5
	v_cvt_pk_bf16_f32 v5, v20, v21
	v_pk_mul_f32 v[16:17], v[16:17], v[24:25] op_sel_hi:[1,0]
	v_pk_mul_f32 v[20:21], v[22:23], v[26:27]
	v_lshlrev_b32_e32 v22, 16, v7
	v_and_b32_e32 v23, 0xffff0000, v7
	v_mul_f32_e32 v6, 0xbfb8aa3b, v22
	v_exp_f32_e32 v25, v6
	v_mul_f32_e32 v6, 0xbfb8aa3b, v23
	v_exp_f32_e32 v26, v6
	s_waitcnt vmcnt(0)
	v_pk_mul_f32 v[16:17], v[34:35], v[16:17]
	v_pk_mul_f32 v[18:19], v[18:19], v[24:25] op_sel_hi:[1,0]
	v_pk_mul_f32 v[6:7], v[20:21], v[16:17]
	v_add_f32_e32 v16, 1.0, v25
	v_add_f32_e32 v17, 1.0, v26
	v_rcp_f32_e32 v16, v16
	v_rcp_f32_e32 v17, v17
	v_pk_mul_f32 v[18:19], v[36:37], v[18:19]
	v_cvt_pk_bf16_f32 v6, v6, v7
	v_lshlrev_b32_e32 v20, 16, v0
	v_pk_mul_f32 v[16:17], v[16:17], v[22:23]
	v_and_b32_e32 v21, 0xffff0000, v0
	v_pk_mul_f32 v[16:17], v[16:17], v[18:19]
	v_mul_f32_e32 v0, 0xbfb8aa3b, v20
	v_cvt_pk_bf16_f32 v7, v16, v17
	v_add_co_u32_e32 v16, vcc, s10, v30
	v_exp_f32_e32 v0, v0
	s_nop 0
	v_addc_co_u32_e32 v17, vcc, 0, v31, vcc
	global_store_dwordx4 v[16:17], v[4:7], off offset:1024
	global_load_dwordx4 v[4:7], v42, s[20:21] offset:32
	s_nop 0
	global_load_dwordx4 v[16:19], v42, s[20:21] offset:48
	v_mul_f32_e32 v22, 0xbfb8aa3b, v21
	v_exp_f32_e32 v23, v22
	v_add_f32_e32 v0, 1.0, v0
	v_rcp_f32_e32 v22, v0
	v_pk_mul_f32 v[12:13], v[12:13], v[24:25] op_sel_hi:[1,0]
	v_add_f32_e32 v0, 1.0, v23
	v_rcp_f32_e32 v23, v0
	s_mov_b64 s[10:11], 0x32200400
	v_lshl_add_u64 v[26:27], v[30:31], 0, s[10:11]
	s_waitcnt vmcnt(1)
	v_pk_mul_f32 v[4:5], v[12:13], v[4:5]
	v_pk_mul_f32 v[12:13], v[22:23], v[20:21]
	v_lshlrev_b32_e32 v20, 16, v1
	v_and_b32_e32 v21, 0xffff0000, v1
	v_mul_f32_e32 v0, 0xbfb8aa3b, v20
	v_exp_f32_e32 v22, v0
	v_mul_f32_e32 v0, 0xbfb8aa3b, v21
	v_exp_f32_e32 v23, v0
	v_pk_mul_f32 v[0:1], v[12:13], v[4:5]
	v_pk_mul_f32 v[12:13], v[14:15], v[24:25] op_sel_hi:[1,0]
	v_add_f32_e32 v4, 1.0, v22
	v_pk_mul_f32 v[6:7], v[12:13], v[6:7]
	v_lshlrev_b32_e32 v12, 16, v2
	v_add_f32_e32 v5, 1.0, v23
	v_cvt_pk_bf16_f32 v0, v0, v1
	v_and_b32_e32 v13, 0xffff0000, v2
	v_mul_f32_e32 v1, 0xbfb8aa3b, v12
	v_rcp_f32_e32 v4, v4
	v_rcp_f32_e32 v5, v5
	v_exp_f32_e32 v1, v1
	v_mul_f32_e32 v2, 0xbfb8aa3b, v13
	v_exp_f32_e32 v2, v2
	v_pk_mul_f32 v[4:5], v[4:5], v[20:21]
	v_add_f32_e32 v1, 1.0, v1
	v_pk_mul_f32 v[4:5], v[4:5], v[6:7]
	v_rcp_f32_e32 v6, v1
	v_add_f32_e32 v1, 1.0, v2
	v_rcp_f32_e32 v7, v1
	v_cvt_pk_bf16_f32 v1, v4, v5
	v_pk_mul_f32 v[4:5], v[8:9], v[24:25] op_sel_hi:[1,0]
	v_lshlrev_b32_e32 v8, 16, v3
	v_and_b32_e32 v9, 0xffff0000, v3
	v_mul_f32_e32 v2, 0xbfb8aa3b, v8
	v_pk_mul_f32 v[6:7], v[6:7], v[12:13]
	v_exp_f32_e32 v12, v2
	v_mul_f32_e32 v2, 0xbfb8aa3b, v9
	v_exp_f32_e32 v13, v2
	s_waitcnt vmcnt(0)
	v_pk_mul_f32 v[4:5], v[4:5], v[16:17]
	s_nop 0
	v_pk_mul_f32 v[2:3], v[6:7], v[4:5]
	v_add_f32_e32 v4, 1.0, v12
	v_add_f32_e32 v5, 1.0, v13
	v_rcp_f32_e32 v4, v4
	v_rcp_f32_e32 v5, v5
	v_pk_mul_f32 v[6:7], v[10:11], v[24:25] op_sel_hi:[1,0]
	v_cvt_pk_bf16_f32 v2, v2, v3
	v_pk_mul_f32 v[6:7], v[6:7], v[18:19]
	v_pk_mul_f32 v[4:5], v[4:5], v[8:9]
	s_nop 0
	v_pk_mul_f32 v[4:5], v[4:5], v[6:7]
	s_nop 0
	v_cvt_pk_bf16_f32 v3, v4, v5
	global_store_dwordx4 v[26:27], v[0:3], off offset:16
	s_waitcnt lgkmcnt(0)
	s_barrier
	s_cbranch_scc1 .LBB0_150
; #define LAS __attribute__((address_space(3)))
; __device__ __forceinline__ int otid() { int t = threadIdx.x; asm volatile("" : "+v"(t)); return t; }
; __device__ __forceinline__ float bflo(unsigned w) { return __uint_as_float(w << 16); }
; __device__ __forceinline__ float bfhi(unsigned w) { return __uint_as_float(w & 0xffff0000u); }
; __device__ __forceinline__ void gla_gates(CP P, const bf16_t* PQ, int m0, int h, LAS unsigned char* lds) {
;     ...
;     { const int idx = tid * 4, t = idx >> 5, r = idx & 31; const uint2 raw = *(const uint2*)(PQ + (size_t)(m0 + t) * 1792 + 1536 + r);
;         *(LAS f32x4*)(gl + idx) = (f32x4){bflo(raw.x), bfhi(raw.x), bflo(raw.y), bfhi(raw.y)}; }
;     float w[16];
; #pragma unroll
;     for (int r = 0; r < 16; ++r) w[r] = P->in[18][(dir * 16 + r) * 256 + h * 64 + d];
;     const float b = P->in[19][dir * 256 + h * 64 + d];
; __device__ void gla_c_unit(CP P, int unit, LAS unsigned char* lds) {
;     const int c = unit & 127, h = (unit >> 7) & 3, b = unit >> 9, m0 = b * 8192 + c * 64;
;     const bf16_t* PQ = (const bf16_t*)(P->ws + OFF_PQ); const bf16_t* GST = (const bf16_t*)(P->ws + OFF_GST); bf16_t* MIX = (bf16_t*)(P->ws + OFF_MIX);
;     const int tid = otid(), lane = tid & 63, wid = tid >> 6;
;     const int t = tid >> 3, d8 = (tid & 7) * 8, v16 = (tid & 7) * 16;
;     const uint4 rq = *(const uint4*)(PQ + (size_t)(m0 + t) * 1792 + h * 64 + d8), rk = *(const uint4*)(PQ + (size_t)(m0 + t) * 1792 + 256 + h * 64 + d8);
;     const uint4 vr0 = *(const uint4*)(PQ + (size_t)(m0 + t) * 1792 + 512 + h * 128 + v16), vr1 = *(const uint4*)(PQ + (size_t)(m0 + t) * 1792 + 512 + h * 128 + v16 + 8);
;     const uint4 ogr0 = *(const uint4*)(PQ + (size_t)(m0 + t) * 1792 + 1024 + h * 128 + v16), ogr1 = *(const uint4*)(PQ + (size_t)(m0 + t) * 1792 + 1024 + h * 128 + v16 + 8);
;     uint4 sr[4];
; #pragma unroll
;     for (int i = 0; i < 4; ++i) { const int idx = tid + i * NTHR, v8 = (idx & 15) * 8, d = (idx >> 4) & 63, dir = idx >> 10;
;         sr[i] = *(const uint4*)(GST + ((size_t)(((b * 4 + h) * 2 + dir) * 128 + c)) * 8192 + d * 128 + v8); }
;     gla_gates(P, PQ, m0, h, lds);
.LBB0_172:
	s_and_b32 s18, s17, 0x7f
	s_ashr_i32 s20, s17, 9
	s_lshl_b32 s10, s20, 13
	s_lshl_b32 s11, s18, 6
	v_mov_b32_e32 v74, v191
	s_or_b32 s21, s10, s11
	s_bfe_u32 s19, s17, 0x20007
	v_ashrrev_i32_e32 v41, 3, v74
	v_add_u32_e32 v40, s21, v41
	v_mov_b64_e32 v[44:45], s[14:15]
	v_mad_i64_i32 v[0:1], s[10:11], v40, s81, v[44:45]
	s_lshl_b32 s66, s19, 7
	s_lshl_b32 s12, s19, 8
	s_mov_b32 s13, s67
	v_lshl_add_u64 v[2:3], v[0:1], 0, s[66:67]
	v_lshl_add_u64 v[0:1], v[0:1], 0, s[12:13]
	s_lshl_b32 s11, s20, 3
	s_lshl_b32 s12, s19, 1
	v_add_u32_e32 v76, 0x200, v74
	v_add_u32_e32 v77, 0x400, v74
	v_add_u32_e32 v78, 0x600, v74
	s_or_b32 s11, s12, s11
	v_ashrrev_i32_e32 v16, 10, v74
	v_ashrrev_i32_e32 v20, 10, v76
	v_ashrrev_i32_e32 v26, 10, v77
	v_ashrrev_i32_e32 v30, 10, v78
	v_add_u32_e32 v16, s11, v16
	v_add_u32_e32 v20, s11, v20
	v_add_u32_e32 v26, s11, v26
	v_add_u32_e32 v30, s11, v30
	v_and_b32_e32 v79, 7, v74
	v_lshl_or_b32 v16, v16, 7, s18
	v_lshl_or_b32 v20, v20, 7, s18
	v_lshl_or_b32 v26, v26, 7, s18
	v_lshl_or_b32 v30, v30, 7, s18
	v_lshlrev_b32_e32 v42, 4, v79
	v_mov_b32_e32 v43, v184
	v_ashrrev_i32_e32 v17, 31, v16
	v_ashrrev_i32_e32 v21, 31, v20
	v_ashrrev_i32_e32 v27, 31, v26
	v_ashrrev_i32_e32 v31, 31, v30
	v_lshl_add_u64 v[2:3], v[2:3], 0, v[42:43]
	v_lshlrev_b32_e32 v43, 3, v74
	v_lshlrev_b64 v[16:17], 14, v[16:17]
	v_lshlrev_b32_e32 v18, 4, v74
	v_lshlrev_b64 v[20:21], 14, v[20:21]
	v_lshlrev_b32_e32 v22, 4, v76
	v_lshlrev_b64 v[26:27], 14, v[26:27]
	v_lshlrev_b64 v[30:31], 14, v[30:31]
	v_lshlrev_b32_e32 v46, 4, v78
	v_and_b32_e32 v75, 0x78, v43
	v_lshl_add_u64 v[16:17], s[44:45], 0, v[16:17]
	v_and_b32_e32 v24, 0x3f00, v18
	v_mov_b32_e32 v25, v184
	v_lshl_add_u64 v[20:21], s[44:45], 0, v[20:21]
	v_and_b32_e32 v22, 0x3f00, v22
	v_mov_b32_e32 v23, v184
	v_lshl_add_u64 v[26:27], s[44:45], 0, v[26:27]
	v_lshl_add_u64 v[30:31], s[44:45], 0, v[30:31]
	v_and_b32_e32 v46, 0x3f00, v46
	v_mov_b32_e32 v47, v184
	v_mov_b64_e32 v[102:103], v[2:3]
	v_lshlrev_b32_e32 v2, 5, v79
	v_mov_b32_e32 v3, v184
	v_lshl_add_u64 v[16:17], v[16:17], 0, v[24:25]
	v_lshlrev_b32_e32 v28, 1, v75
	v_mov_b32_e32 v29, v184
	v_lshl_add_u64 v[20:21], v[20:21], 0, v[22:23]
	v_lshl_add_u64 v[24:25], v[26:27], 0, v[24:25]
	v_lshl_add_u64 v[30:31], v[30:31], 0, v[46:47]
	v_lshl_add_u64 v[4:5], v[0:1], 0, v[2:3]
	v_lshl_add_u64 v[16:17], v[16:17], 0, v[28:29]
	v_lshl_add_u64 v[20:21], v[20:21], 0, v[28:29]
	v_lshl_add_u64 v[24:25], v[24:25], 0, v[28:29]
	v_lshl_add_u64 v[28:29], v[30:31], 0, v[28:29]
	v_mov_b32_e32 v83, v191
	s_lshl_b32 s10, s19, 6
	s_movk_i32 s11, 0x1000
	s_nop 0
	v_ashrrev_i32_e32 v46, 3, v83
	v_add_u32_e32 v46, s21, v46
	v_mad_i64_i32 v[44:45], s[12:13], v46, s81, v[44:45]
	v_lshlrev_b32_e32 v46, 3, v83
	v_and_b32_e32 v46, 56, v46
	v_lshl_add_u64 v[44:45], v[44:45], 0, v[46:47]
	global_load_dwordx2 v[46:47], v[44:45], off offset:3072
	s_load_dwordx4 s[20:23], s[0:1], 0x90
	v_ashrrev_i32_e32 v80, 8, v83
	v_lshl_add_u32 v48, v83, 4, 0
	v_and_b32_e32 v81, 63, v83
	v_and_b32_e32 v84, 0xffffff00, v83
	s_waitcnt lgkmcnt(0)
	v_mov_b32_e32 v54, s22
	v_mov_b32_e32 v55, s23
	v_bfe_u32 v82, v83, 6, 2
	s_waitcnt vmcnt(0)
	v_lshlrev_b32_e32 v44, 16, v46
	v_and_b32_e32 v45, 0xffff0000, v46
	v_lshlrev_b32_e32 v46, 16, v47
	v_and_b32_e32 v47, 0xffff0000, v47
	ds_write_b128 v48, v[44:47]
	v_lshlrev_b32_e32 v46, 12, v80
	v_or3_b32 v46, v46, s10, v81
	v_mov_b32_e32 v44, s20
	v_mov_b32_e32 v45, s21
	v_ashrrev_i32_e32 v47, 31, v46
	v_lshl_add_u64 v[62:63], v[46:47], 2, v[44:45]
	v_add_co_u32_e32 v46, vcc, s11, v62
	s_movk_i32 s11, 0x3000
	s_nop 0
	v_addc_co_u32_e32 v47, vcc, 0, v63, vcc
	v_add_co_u32_e32 v64, vcc, s88, v62
	global_load_dword v50, v[62:63], off
	global_load_dword v56, v[62:63], off offset:1024
	global_load_dword v48, v[62:63], off offset:2048
	global_load_dword v44, v[62:63], off offset:3072
	v_addc_co_u32_e32 v65, vcc, 0, v63, vcc
	v_add_co_u32_e32 v62, vcc, s11, v62
	global_load_dword v51, v[64:65], off offset:-4096
	global_load_dword v57, v[46:47], off offset:1024
	global_load_dword v49, v[46:47], off offset:2048
	global_load_dword v45, v[46:47], off offset:3072
	global_load_dword v58, v[64:65], off
	global_load_dword v60, v[64:65], off offset:1024
	global_load_dword v52, v[64:65], off offset:2048
	s_nop 0
	global_load_dword v46, v[64:65], off offset:3072
	v_addc_co_u32_e32 v63, vcc, 0, v63, vcc
	global_load_dword v59, v[62:63], off
	global_load_dword v61, v[62:63], off offset:1024
	global_load_dword v53, v[62:63], off offset:2048
	global_load_dword v47, v[62:63], off offset:3072
	v_or3_b32 v62, v81, s10, v84
	v_ashrrev_i32_e32 v63, 31, v62
	v_lshl_add_u64 v[54:55], v[62:63], 2, v[54:55]
	global_load_dword v85, v[54:55], off
	global_load_dwordx4 v[36:39], v[102:103], off
	global_load_dwordx4 v[32:35], v[102:103], off offset:512
	global_load_dwordx4 v[8:11], v[4:5], off offset:1040
	global_load_dwordx4 v[12:15], v[4:5], off offset:1024
	global_load_dwordx4 v[0:3], v[4:5], off offset:2064
	s_nop 0
	global_load_dwordx4 v[4:7], v[4:5], off offset:2048
	global_load_dwordx4 v[16:19], v[16:17], off
	global_load_dwordx4 v[20:23], v[20:21], off
	s_nop 0
	global_load_dwordx4 v[24:27], v[24:25], off
	s_nop 0
	global_load_dwordx4 v[28:31], v[28:29], off
	v_lshlrev_b32_e32 v54, 11, v82
	v_lshlrev_b32_e32 v55, 6, v80
	s_waitcnt lgkmcnt(0)
	s_barrier
; #define LAS __attribute__((address_space(3)))
; __device__ __forceinline__ void lds_barrier() { asm volatile("s_waitcnt lgkmcnt(0)" ::: "memory"); __builtin_amdgcn_s_barrier(); asm volatile("" ::: "memory"); }
; __device__ __forceinline__ void gla_gates(CP P, const bf16_t* PQ, int m0, int h, LAS unsigned char* lds) {
;     ...
;     float w[16];
; #pragma unroll
;     for (int r = 0; r < 16; ++r) w[r] = P->in[18][(dir * 16 + r) * 256 + h * 64 + d];
;     const float b = P->in[19][dir * 256 + h * 64 + d];
;     lds_barrier();
;     float c[16];
; #pragma unroll
;     for (int i = 0; i < 16; ++i) { const int t = tq * 16 + i; float z = b;
; #pragma unroll
;         for (int r4 = 0; r4 < 4; ++r4) { const f32x4 g4 = *(const LAS f32x4*)(gl + t * 32 + dir * 16 + r4 * 4);
;             z += g4[0] * w[r4 * 4] + g4[1] * w[r4 * 4 + 1] + g4[2] * w[r4 * 4 + 2] + g4[3] * w[r4 * 4 + 3]; }
;         c[i] = (fminf(z, 0.f) - __logf(1.0f + __expf(-fabsf(z)))) * (1.0f / 16.0f); }
	v_add3_u32 v86, 0, v54, v55
	ds_read_b128 v[62:65], v86
	ds_read_b128 v[66:69], v86 offset:16
	ds_read_b128 v[70:73], v86 offset:32
	ds_read_b128 v[88:91], v86 offset:48
	s_movk_i32 s10, 0x100
	s_waitcnt lgkmcnt(3)
	v_mov_b32_e32 v54, v62
	s_waitcnt lgkmcnt(2)
	v_mov_b32_e32 v55, v66
	v_mov_b32_e32 v66, v63
	s_waitcnt vmcnt(21)
	v_pk_mul_f32 v[62:63], v[56:57], v[66:67]
	s_nop 0
	v_pk_fma_f32 v[54:55], v[50:51], v[54:55], v[62:63]
	v_mov_b32_e32 v62, v64
	v_mov_b32_e32 v63, v68
	s_waitcnt vmcnt(20)
	v_pk_fma_f32 v[54:55], v[48:49], v[62:63], v[54:55]
	v_mov_b32_e32 v68, v65
	s_waitcnt vmcnt(19)
	v_pk_fma_f32 v[54:55], v[44:45], v[68:69], v[54:55]
	s_waitcnt vmcnt(10)
	v_add_f32_e32 v54, v85, v54
	v_add_f32_e32 v64, v54, v55
	s_waitcnt lgkmcnt(0)
	v_mov_b32_e32 v55, v88
	v_mov_b32_e32 v88, v71
	v_mov_b32_e32 v54, v70
	v_pk_mul_f32 v[62:63], v[60:61], v[88:89]
	s_nop 0
	v_pk_fma_f32 v[54:55], v[58:59], v[54:55], v[62:63]
	v_mov_b32_e32 v62, v72
	v_mov_b32_e32 v63, v90
	v_pk_fma_f32 v[54:55], v[52:53], v[62:63], v[54:55]
	v_mov_b32_e32 v90, v73
	v_pk_fma_f32 v[54:55], v[46:47], v[90:91], v[54:55]
	s_nop 0
	v_add_f32_e32 v54, v64, v54
	v_add_f32_e32 v55, v54, v55
	v_min_f32_e32 v54, 0, v55
	v_mul_f32_e64 v55, |v55|, s33
	v_exp_f32_e32 v55, v55
	s_nop 0
	v_add_f32_e32 v55, 1.0, v55
	v_cmp_gt_f32_e32 vcc, s80, v55
	s_nop 1
	v_cndmask_b32_e64 v62, 0, 32, vcc
	v_ldexp_f32 v55, v55, v62
	v_log_f32_e32 v55, v55
	s_nop 0
	v_mul_f32_e32 v62, 0x3f317217, v55
	v_fma_f32 v62, v55, s92, -v62
	v_fmac_f32_e32 v62, 0x3377d1cf, v55
	v_fmac_f32_e32 v62, 0x3f317217, v55
	v_cmp_lt_f32_e64 s[40:41], |v55|, s93
	s_nop 1
	v_cndmask_b32_e64 v55, v55, v62, s[40:41]
	v_cndmask_b32_e32 v62, 0, v231, vcc
	v_sub_f32_e32 v70, v55, v62
	ds_read_b128 v[62:65], v86 offset:128
	ds_read_b128 v[66:69], v86 offset:144
	s_waitcnt lgkmcnt(1)
	v_mov_b32_e32 v72, v62
	s_waitcnt lgkmcnt(0)
	v_mov_b32_e32 v73, v66
	v_mov_b32_e32 v66, v63
	v_pk_mul_f32 v[62:63], v[56:57], v[66:67]
	v_mov_b32_e32 v66, v64
	v_pk_fma_f32 v[62:63], v[50:51], v[72:73], v[62:63]
	v_mov_b32_e32 v67, v68
	v_pk_fma_f32 v[62:63], v[48:49], v[66:67], v[62:63]
	v_mov_b32_e32 v68, v65
	v_pk_fma_f32 v[62:63], v[44:45], v[68:69], v[62:63]
	s_nop 0
	v_add_f32_e32 v55, v85, v62
	v_add_f32_e32 v55, v55, v63
	ds_read_b128 v[62:65], v86 offset:160
	ds_read_b128 v[66:69], v86 offset:176
	s_waitcnt lgkmcnt(1)
	v_mov_b32_e32 v72, v62
	s_waitcnt lgkmcnt(0)
	v_mov_b32_e32 v73, v66
	v_mov_b32_e32 v66, v63
	v_pk_mul_f32 v[62:63], v[60:61], v[66:67]
	v_mov_b32_e32 v66, v64
	v_pk_fma_f32 v[62:63], v[58:59], v[72:73], v[62:63]
	v_mov_b32_e32 v67, v68
	v_pk_fma_f32 v[62:63], v[52:53], v[66:67], v[62:63]
	v_mov_b32_e32 v68, v65
	v_pk_fma_f32 v[62:63], v[46:47], v[68:69], v[62:63]
	s_nop 0
	v_add_f32_e32 v55, v55, v62
	v_add_f32_e32 v62, v55, v63
	v_min_f32_e32 v55, 0, v62
	v_mul_f32_e64 v62, |v62|, s33
	v_exp_f32_e32 v62, v62
	s_nop 0
	v_add_f32_e32 v62, 1.0, v62
	v_cmp_gt_f32_e32 vcc, s80, v62
	s_nop 1
	v_cndmask_b32_e64 v63, 0, 32, vcc
	v_ldexp_f32 v62, v62, v63
	v_log_f32_e32 v62, v62
	s_nop 0
	v_mul_f32_e32 v63, 0x3f317217, v62
	v_fma_f32 v63, v62, s92, -v63
	v_fmac_f32_e32 v63, 0x3377d1cf, v62
	v_fmac_f32_e32 v63, 0x3f317217, v62
	v_cmp_lt_f32_e64 s[40:41], |v62|, s93
	s_nop 1
	v_cndmask_b32_e64 v62, v62, v63, s[40:41]
	v_cndmask_b32_e32 v63, 0, v231, vcc
	v_sub_f32_e32 v71, v62, v63
	ds_read_b128 v[62:65], v86 offset:256
	ds_read_b128 v[66:69], v86 offset:272
	v_pk_add_f32 v[54:55], v[54:55], v[70:71] neg_lo:[0,1] neg_hi:[0,1]
	s_waitcnt lgkmcnt(1)
	v_mov_b32_e32 v70, v62
	s_waitcnt lgkmcnt(0)
	v_mov_b32_e32 v71, v66
	v_mov_b32_e32 v66, v63
	v_pk_mul_f32 v[62:63], v[56:57], v[66:67]
	v_mov_b32_e32 v66, v64
	v_pk_fma_f32 v[62:63], v[50:51], v[70:71], v[62:63]
	v_mov_b32_e32 v67, v68
	v_pk_fma_f32 v[62:63], v[48:49], v[66:67], v[62:63]
	v_mov_b32_e32 v68, v65
	v_pk_fma_f32 v[62:63], v[44:45], v[68:69], v[62:63]
	v_pk_mul_f32 v[54:55], v[54:55], s[78:79] op_sel_hi:[1,0]
	v_add_f32_e32 v62, v85, v62
	v_add_f32_e32 v72, v62, v63
	ds_read_b128 v[62:65], v86 offset:288
	ds_read_b128 v[66:69], v86 offset:304
	s_waitcnt lgkmcnt(1)
	v_mov_b32_e32 v70, v62
	s_waitcnt lgkmcnt(0)
	v_mov_b32_e32 v71, v66
	v_mov_b32_e32 v66, v63
	v_pk_mul_f32 v[62:63], v[60:61], v[66:67]
	v_mov_b32_e32 v66, v64
	v_pk_fma_f32 v[62:63], v[58:59], v[70:71], v[62:63]
	v_mov_b32_e32 v67, v68
	v_pk_fma_f32 v[62:63], v[52:53], v[66:67], v[62:63]
	v_mov_b32_e32 v68, v65
	v_pk_fma_f32 v[62:63], v[46:47], v[68:69], v[62:63]
	s_nop 0
	v_add_f32_e32 v62, v72, v62
	v_add_f32_e32 v62, v62, v63
	v_min_f32_e32 v70, 0, v62
	v_mul_f32_e64 v62, |v62|, s33
	v_exp_f32_e32 v62, v62
	s_nop 0
	v_add_f32_e32 v62, 1.0, v62
	v_cmp_gt_f32_e32 vcc, s80, v62
	s_nop 1
	v_cndmask_b32_e64 v63, 0, 32, vcc
	v_ldexp_f32 v62, v62, v63
	v_log_f32_e32 v62, v62
	s_nop 0
	v_mul_f32_e32 v63, 0x3f317217, v62
	v_fma_f32 v63, v62, s92, -v63
	v_fmac_f32_e32 v63, 0x3377d1cf, v62
	v_fmac_f32_e32 v63, 0x3f317217, v62
	v_cmp_lt_f32_e64 s[40:41], |v62|, s93
	s_nop 1
	v_cndmask_b32_e64 v62, v62, v63, s[40:41]
	v_cndmask_b32_e32 v63, 0, v231, vcc
	v_sub_f32_e32 v72, v62, v63
	ds_read_b128 v[62:65], v86 offset:384
	ds_read_b128 v[66:69], v86 offset:400
	s_waitcnt lgkmcnt(1)
	v_mov_b32_e32 v88, v62
	s_waitcnt lgkmcnt(0)
	v_mov_b32_e32 v89, v66
	v_mov_b32_e32 v66, v63
	v_pk_mul_f32 v[62:63], v[56:57], v[66:67]
	v_mov_b32_e32 v66, v64
	v_pk_fma_f32 v[62:63], v[50:51], v[88:89], v[62:63]
	v_mov_b32_e32 v67, v68
	v_pk_fma_f32 v[62:63], v[48:49], v[66:67], v[62:63]
	v_mov_b32_e32 v68, v65
	v_pk_fma_f32 v[62:63], v[44:45], v[68:69], v[62:63]
	s_nop 0
	v_add_f32_e32 v62, v85, v62
	v_add_f32_e32 v71, v62, v63
	ds_read_b128 v[62:65], v86 offset:416
	ds_read_b128 v[66:69], v86 offset:432
	s_waitcnt lgkmcnt(1)
; #define LAS __attribute__((address_space(3)))
; __device__ __forceinline__ void gla_gates(CP P, const bf16_t* PQ, int m0, int h, LAS unsigned char* lds) {
;     ...
;     for (int i = 0; i < 16; ++i) { const int t = tq * 16 + i; float z = b;
; #pragma unroll
;         for (int r4 = 0; r4 < 4; ++r4) { const f32x4 g4 = *(const LAS f32x4*)(gl + t * 32 + dir * 16 + r4 * 4);
;             z += g4[0] * w[r4 * 4] + g4[1] * w[r4 * 4 + 1] + g4[2] * w[r4 * 4 + 2] + g4[3] * w[r4 * 4 + 3]; }
;         c[i] = (fminf(z, 0.f) - __logf(1.0f + __expf(-fabsf(z)))) * (1.0f / 16.0f); }
	v_mov_b32_e32 v88, v62
	s_waitcnt lgkmcnt(0)
	v_mov_b32_e32 v89, v66
	v_mov_b32_e32 v66, v63
	v_pk_mul_f32 v[62:63], v[60:61], v[66:67]
	v_mov_b32_e32 v66, v64
	v_pk_fma_f32 v[62:63], v[58:59], v[88:89], v[62:63]
	v_mov_b32_e32 v67, v68
	v_pk_fma_f32 v[62:63], v[52:53], v[66:67], v[62:63]
	v_mov_b32_e32 v68, v65
	v_pk_fma_f32 v[62:63], v[46:47], v[68:69], v[62:63]
	s_nop 0
	v_add_f32_e32 v62, v71, v62
	v_add_f32_e32 v62, v62, v63
	v_min_f32_e32 v71, 0, v62
	v_mul_f32_e64 v62, |v62|, s33
	v_exp_f32_e32 v62, v62
	s_nop 0
	v_add_f32_e32 v62, 1.0, v62
	v_cmp_gt_f32_e32 vcc, s80, v62
	s_nop 1
	v_cndmask_b32_e64 v63, 0, 32, vcc
	v_ldexp_f32 v62, v62, v63
	v_log_f32_e32 v62, v62
	s_nop 0
	v_mul_f32_e32 v63, 0x3f317217, v62
	v_fma_f32 v63, v62, s92, -v63
	v_fmac_f32_e32 v63, 0x3377d1cf, v62
	v_fmac_f32_e32 v63, 0x3f317217, v62
	v_cmp_lt_f32_e64 s[40:41], |v62|, s93
	s_nop 1
	v_cndmask_b32_e64 v62, v62, v63, s[40:41]
	v_cndmask_b32_e32 v63, 0, v231, vcc
	v_sub_f32_e32 v73, v62, v63
	v_pk_add_f32 v[62:63], v[70:71], v[72:73] neg_lo:[0,1] neg_hi:[0,1]
	ds_read_b128 v[64:67], v86 offset:512
	ds_read_b128 v[68:71], v86 offset:528
	v_pk_mul_f32 v[62:63], v[62:63], s[78:79] op_sel_hi:[1,0]
	s_waitcnt lgkmcnt(1)
	v_mov_b32_e32 v72, v64
	s_waitcnt lgkmcnt(0)
	v_mov_b32_e32 v73, v68
	v_mov_b32_e32 v68, v65
	v_pk_mul_f32 v[64:65], v[56:57], v[68:69]
	v_mov_b32_e32 v68, v66
	v_pk_fma_f32 v[64:65], v[50:51], v[72:73], v[64:65]
	v_mov_b32_e32 v69, v70
	v_pk_fma_f32 v[64:65], v[48:49], v[68:69], v[64:65]
	v_mov_b32_e32 v70, v67
	v_pk_fma_f32 v[64:65], v[44:45], v[70:71], v[64:65]
	s_nop 0
	v_add_f32_e32 v64, v85, v64
	v_add_f32_e32 v87, v64, v65
	ds_read_b128 v[64:67], v86 offset:544
	ds_read_b128 v[68:71], v86 offset:560
	s_waitcnt lgkmcnt(1)
	v_mov_b32_e32 v72, v64
	s_waitcnt lgkmcnt(0)
	v_mov_b32_e32 v73, v68
	v_mov_b32_e32 v68, v65
	v_pk_mul_f32 v[64:65], v[60:61], v[68:69]
	v_mov_b32_e32 v68, v66
	v_pk_fma_f32 v[64:65], v[58:59], v[72:73], v[64:65]
	v_mov_b32_e32 v69, v70
	v_pk_fma_f32 v[64:65], v[52:53], v[68:69], v[64:65]
	v_mov_b32_e32 v70, v67
	v_pk_fma_f32 v[64:65], v[46:47], v[70:71], v[64:65]
	s_nop 0
	v_add_f32_e32 v64, v87, v64
	v_add_f32_e32 v64, v64, v65
	v_min_f32_e32 v72, 0, v64
	v_mul_f32_e64 v64, |v64|, s33
	v_exp_f32_e32 v64, v64
	s_nop 0
	v_add_f32_e32 v64, 1.0, v64
	v_cmp_gt_f32_e32 vcc, s80, v64
	s_nop 1
	v_cndmask_b32_e64 v65, 0, 32, vcc
	v_ldexp_f32 v64, v64, v65
	v_log_f32_e32 v64, v64
	s_nop 0
	v_mul_f32_e32 v65, 0x3f317217, v64
	v_fma_f32 v65, v64, s92, -v65
	v_fmac_f32_e32 v65, 0x3377d1cf, v64
	v_fmac_f32_e32 v65, 0x3f317217, v64
	v_cmp_lt_f32_e64 s[40:41], |v64|, s93
	s_nop 1
	v_cndmask_b32_e64 v64, v64, v65, s[40:41]
	v_cndmask_b32_e32 v65, 0, v231, vcc
	v_sub_f32_e32 v88, v64, v65
	ds_read_b128 v[64:67], v86 offset:640
	ds_read_b128 v[68:71], v86 offset:656
	s_waitcnt lgkmcnt(1)
	v_mov_b32_e32 v90, v64
	s_waitcnt lgkmcnt(0)
	v_mov_b32_e32 v91, v68
	v_mov_b32_e32 v68, v65
	v_pk_mul_f32 v[64:65], v[56:57], v[68:69]
	v_mov_b32_e32 v68, v66
	v_pk_fma_f32 v[64:65], v[50:51], v[90:91], v[64:65]
	v_mov_b32_e32 v69, v70
	v_pk_fma_f32 v[64:65], v[48:49], v[68:69], v[64:65]
	v_mov_b32_e32 v70, v67
	v_pk_fma_f32 v[64:65], v[44:45], v[70:71], v[64:65]
	s_nop 0
	v_add_f32_e32 v64, v85, v64
	v_add_f32_e32 v73, v64, v65
	ds_read_b128 v[64:67], v86 offset:672
	ds_read_b128 v[68:71], v86 offset:688
	s_waitcnt lgkmcnt(1)
	v_mov_b32_e32 v90, v64
	s_waitcnt lgkmcnt(0)
	v_mov_b32_e32 v91, v68
	v_mov_b32_e32 v68, v65
	v_pk_mul_f32 v[64:65], v[60:61], v[68:69]
	v_mov_b32_e32 v68, v66
	v_pk_fma_f32 v[64:65], v[58:59], v[90:91], v[64:65]
	v_mov_b32_e32 v69, v70
	v_pk_fma_f32 v[64:65], v[52:53], v[68:69], v[64:65]
	v_mov_b32_e32 v70, v67
	v_pk_fma_f32 v[64:65], v[46:47], v[70:71], v[64:65]
	s_nop 0
	v_add_f32_e32 v64, v73, v64
	v_add_f32_e32 v64, v64, v65
	v_min_f32_e32 v73, 0, v64
	v_mul_f32_e64 v64, |v64|, s33
	v_exp_f32_e32 v64, v64
	s_nop 0
	v_add_f32_e32 v64, 1.0, v64
	v_cmp_gt_f32_e32 vcc, s80, v64
	s_nop 1
	v_cndmask_b32_e64 v65, 0, 32, vcc
	v_ldexp_f32 v64, v64, v65
	v_log_f32_e32 v64, v64
	s_nop 0
	v_mul_f32_e32 v65, 0x3f317217, v64
	v_fma_f32 v65, v64, s92, -v65
	v_fmac_f32_e32 v65, 0x3377d1cf, v64
	v_fmac_f32_e32 v65, 0x3f317217, v64
	v_cmp_lt_f32_e64 s[40:41], |v64|, s93
	s_nop 1
	v_cndmask_b32_e64 v64, v64, v65, s[40:41]
	v_cndmask_b32_e32 v65, 0, v231, vcc
	v_sub_f32_e32 v89, v64, v65
	v_pk_add_f32 v[64:65], v[72:73], v[88:89] neg_lo:[0,1] neg_hi:[0,1]
	ds_read_b128 v[66:69], v86 offset:768
	ds_read_b128 v[70:73], v86 offset:784
	v_pk_mul_f32 v[64:65], v[64:65], s[78:79] op_sel_hi:[1,0]
	s_waitcnt lgkmcnt(1)
	v_mov_b32_e32 v88, v66
	s_waitcnt lgkmcnt(0)
	v_mov_b32_e32 v89, v70
	v_mov_b32_e32 v70, v67
	v_pk_mul_f32 v[66:67], v[56:57], v[70:71]
	v_mov_b32_e32 v70, v68
	v_pk_fma_f32 v[66:67], v[50:51], v[88:89], v[66:67]
	v_mov_b32_e32 v71, v72
	v_pk_fma_f32 v[66:67], v[48:49], v[70:71], v[66:67]
	v_mov_b32_e32 v72, v69
	v_pk_fma_f32 v[66:67], v[44:45], v[72:73], v[66:67]
	s_nop 0
	v_add_f32_e32 v66, v85, v66
	v_add_f32_e32 v87, v66, v67
	ds_read_b128 v[66:69], v86 offset:800
	ds_read_b128 v[70:73], v86 offset:816
	s_waitcnt lgkmcnt(1)
	v_mov_b32_e32 v88, v66
	s_waitcnt lgkmcnt(0)
; #define LAS __attribute__((address_space(3)))
; __device__ __forceinline__ void gla_gates(CP P, const bf16_t* PQ, int m0, int h, LAS unsigned char* lds) {
;     ...
;     for (int i = 0; i < 16; ++i) { const int t = tq * 16 + i; float z = b;
; #pragma unroll
;         for (int r4 = 0; r4 < 4; ++r4) { const f32x4 g4 = *(const LAS f32x4*)(gl + t * 32 + dir * 16 + r4 * 4);
;             z += g4[0] * w[r4 * 4] + g4[1] * w[r4 * 4 + 1] + g4[2] * w[r4 * 4 + 2] + g4[3] * w[r4 * 4 + 3]; }
;         c[i] = (fminf(z, 0.f) - __logf(1.0f + __expf(-fabsf(z)))) * (1.0f / 16.0f); }
	v_mov_b32_e32 v89, v70
	v_mov_b32_e32 v70, v67
	v_pk_mul_f32 v[66:67], v[60:61], v[70:71]
	v_mov_b32_e32 v70, v68
	v_pk_fma_f32 v[66:67], v[58:59], v[88:89], v[66:67]
	v_mov_b32_e32 v71, v72
	v_pk_fma_f32 v[66:67], v[52:53], v[70:71], v[66:67]
	v_mov_b32_e32 v72, v69
	v_pk_fma_f32 v[66:67], v[46:47], v[72:73], v[66:67]
	s_nop 0
	v_add_f32_e32 v66, v87, v66
	v_add_f32_e32 v66, v66, v67
	v_min_f32_e32 v88, 0, v66
	v_mul_f32_e64 v66, |v66|, s33
	v_exp_f32_e32 v66, v66
	s_nop 0
	v_add_f32_e32 v66, 1.0, v66
	v_cmp_gt_f32_e32 vcc, s80, v66
	s_nop 1
	v_cndmask_b32_e64 v67, 0, 32, vcc
	v_ldexp_f32 v66, v66, v67
	v_log_f32_e32 v66, v66
	s_nop 0
	v_mul_f32_e32 v67, 0x3f317217, v66
	v_fma_f32 v67, v66, s92, -v67
	v_fmac_f32_e32 v67, 0x3377d1cf, v66
	v_fmac_f32_e32 v67, 0x3f317217, v66
	v_cmp_lt_f32_e64 s[40:41], |v66|, s93
	s_nop 1
	v_cndmask_b32_e64 v66, v66, v67, s[40:41]
	v_cndmask_b32_e32 v67, 0, v231, vcc
	v_sub_f32_e32 v90, v66, v67
	ds_read_b128 v[66:69], v86 offset:896
	ds_read_b128 v[70:73], v86 offset:912
	s_waitcnt lgkmcnt(1)
	v_mov_b32_e32 v92, v66
	s_waitcnt lgkmcnt(0)
	v_mov_b32_e32 v93, v70
	v_mov_b32_e32 v70, v67
	v_pk_mul_f32 v[66:67], v[56:57], v[70:71]
	v_mov_b32_e32 v70, v68
	v_pk_fma_f32 v[66:67], v[50:51], v[92:93], v[66:67]
	v_mov_b32_e32 v71, v72
	v_pk_fma_f32 v[66:67], v[48:49], v[70:71], v[66:67]
	v_mov_b32_e32 v72, v69
	v_pk_fma_f32 v[66:67], v[44:45], v[72:73], v[66:67]
	s_nop 0
	v_add_f32_e32 v66, v85, v66
	v_add_f32_e32 v87, v66, v67
	ds_read_b128 v[66:69], v86 offset:928
	ds_read_b128 v[70:73], v86 offset:944
	s_waitcnt lgkmcnt(1)
	v_mov_b32_e32 v92, v66
	s_waitcnt lgkmcnt(0)
	v_mov_b32_e32 v93, v70
	v_mov_b32_e32 v70, v67
	v_pk_mul_f32 v[66:67], v[60:61], v[70:71]
	v_mov_b32_e32 v70, v68
	v_pk_fma_f32 v[66:67], v[58:59], v[92:93], v[66:67]
	v_mov_b32_e32 v71, v72
	v_pk_fma_f32 v[66:67], v[52:53], v[70:71], v[66:67]
	v_mov_b32_e32 v72, v69
	v_pk_fma_f32 v[66:67], v[46:47], v[72:73], v[66:67]
	s_nop 0
	v_add_f32_e32 v66, v87, v66
	v_add_f32_e32 v66, v66, v67
	v_min_f32_e32 v89, 0, v66
	v_mul_f32_e64 v66, |v66|, s33
	v_exp_f32_e32 v66, v66
	s_nop 0
	v_add_f32_e32 v66, 1.0, v66
	v_cmp_gt_f32_e32 vcc, s80, v66
	s_nop 1
	v_cndmask_b32_e64 v67, 0, 32, vcc
	v_ldexp_f32 v66, v66, v67
	v_log_f32_e32 v66, v66
	s_nop 0
	v_mul_f32_e32 v67, 0x3f317217, v66
	v_fma_f32 v67, v66, s92, -v67
	v_fmac_f32_e32 v67, 0x3377d1cf, v66
	v_fmac_f32_e32 v67, 0x3f317217, v66
	v_cmp_lt_f32_e64 s[40:41], |v66|, s93
	s_nop 1
	v_cndmask_b32_e64 v66, v66, v67, s[40:41]
	v_cndmask_b32_e32 v67, 0, v231, vcc
	v_sub_f32_e32 v91, v66, v67
	v_pk_add_f32 v[66:67], v[88:89], v[90:91] neg_lo:[0,1] neg_hi:[0,1]
	ds_read_b128 v[68:71], v86 offset:1024
	ds_read_b128 v[88:91], v86 offset:1040
	v_pk_mul_f32 v[66:67], v[66:67], s[78:79] op_sel_hi:[1,0]
	s_waitcnt lgkmcnt(1)
	v_mov_b32_e32 v72, v68
	s_waitcnt lgkmcnt(0)
	v_mov_b32_e32 v73, v88
	v_mov_b32_e32 v88, v69
	v_pk_mul_f32 v[68:69], v[56:57], v[88:89]
	s_nop 0
	v_pk_fma_f32 v[68:69], v[50:51], v[72:73], v[68:69]
	v_mov_b32_e32 v72, v70
	v_mov_b32_e32 v73, v90
	v_pk_fma_f32 v[68:69], v[48:49], v[72:73], v[68:69]
	v_mov_b32_e32 v90, v71
	v_pk_fma_f32 v[68:69], v[44:45], v[90:91], v[68:69]
	s_nop 0
	v_add_f32_e32 v68, v85, v68
	v_add_f32_e32 v87, v68, v69
	ds_read_b128 v[68:71], v86 offset:1056
	ds_read_b128 v[88:91], v86 offset:1072
	s_waitcnt lgkmcnt(1)
	v_mov_b32_e32 v72, v68
	s_waitcnt lgkmcnt(0)
	v_mov_b32_e32 v73, v88
	v_mov_b32_e32 v88, v69
	v_pk_mul_f32 v[68:69], v[60:61], v[88:89]
	s_nop 0
	v_pk_fma_f32 v[68:69], v[58:59], v[72:73], v[68:69]
	v_mov_b32_e32 v72, v70
	v_mov_b32_e32 v73, v90
	v_pk_fma_f32 v[68:69], v[52:53], v[72:73], v[68:69]
	v_mov_b32_e32 v90, v71
	v_pk_fma_f32 v[68:69], v[46:47], v[90:91], v[68:69]
	s_nop 0
	v_add_f32_e32 v68, v87, v68
	v_add_f32_e32 v68, v68, v69
	v_min_f32_e32 v72, 0, v68
	v_mul_f32_e64 v68, |v68|, s33
	v_exp_f32_e32 v68, v68
	s_nop 0
	v_add_f32_e32 v68, 1.0, v68
	v_cmp_gt_f32_e32 vcc, s80, v68
	s_nop 1
	v_cndmask_b32_e64 v69, 0, 32, vcc
	v_ldexp_f32 v68, v68, v69
	v_log_f32_e32 v68, v68
	s_nop 0
	v_mul_f32_e32 v69, 0x3f317217, v68
	v_fma_f32 v69, v68, s92, -v69
	v_fmac_f32_e32 v69, 0x3377d1cf, v68
	v_fmac_f32_e32 v69, 0x3f317217, v68
	v_cmp_lt_f32_e64 s[40:41], |v68|, s93
	s_nop 1
	v_cndmask_b32_e64 v68, v68, v69, s[40:41]
	v_cndmask_b32_e32 v69, 0, v231, vcc
	v_sub_f32_e32 v92, v68, v69
	ds_read_b128 v[68:71], v86 offset:1152
	ds_read_b128 v[88:91], v86 offset:1168
	s_waitcnt lgkmcnt(1)
	v_mov_b32_e32 v94, v68
	s_waitcnt lgkmcnt(0)
	v_mov_b32_e32 v95, v88
	v_mov_b32_e32 v88, v69
	v_pk_mul_f32 v[68:69], v[56:57], v[88:89]
	v_mov_b32_e32 v88, v70
	v_pk_fma_f32 v[68:69], v[50:51], v[94:95], v[68:69]
	v_mov_b32_e32 v89, v90
	v_pk_fma_f32 v[68:69], v[48:49], v[88:89], v[68:69]
	v_mov_b32_e32 v90, v71
	v_pk_fma_f32 v[68:69], v[44:45], v[90:91], v[68:69]
	s_nop 0
	v_add_f32_e32 v68, v85, v68
	v_add_f32_e32 v73, v68, v69
	ds_read_b128 v[68:71], v86 offset:1184
	ds_read_b128 v[88:91], v86 offset:1200
	s_waitcnt lgkmcnt(1)
	v_mov_b32_e32 v94, v68
	s_waitcnt lgkmcnt(0)
	v_mov_b32_e32 v95, v88
	v_mov_b32_e32 v88, v69
	v_pk_mul_f32 v[68:69], v[60:61], v[88:89]
	v_mov_b32_e32 v88, v70
	v_pk_fma_f32 v[68:69], v[58:59], v[94:95], v[68:69]
	v_mov_b32_e32 v89, v90
	v_pk_fma_f32 v[68:69], v[52:53], v[88:89], v[68:69]
	v_mov_b32_e32 v90, v71
	v_pk_fma_f32 v[68:69], v[46:47], v[90:91], v[68:69]
	s_nop 0
	v_add_f32_e32 v68, v73, v68
	v_add_f32_e32 v68, v68, v69
	v_min_f32_e32 v73, 0, v68
	v_mul_f32_e64 v68, |v68|, s33
	v_exp_f32_e32 v68, v68
	s_nop 0
	v_add_f32_e32 v68, 1.0, v68
	v_cmp_gt_f32_e32 vcc, s80, v68
	s_nop 1
	v_cndmask_b32_e64 v69, 0, 32, vcc
	v_ldexp_f32 v68, v68, v69
	v_log_f32_e32 v68, v68
	s_nop 0
	v_mul_f32_e32 v69, 0x3f317217, v68
	v_fma_f32 v69, v68, s92, -v69
	v_fmac_f32_e32 v69, 0x3377d1cf, v68
	v_fmac_f32_e32 v69, 0x3f317217, v68
	v_cmp_lt_f32_e64 s[40:41], |v68|, s93
	s_nop 1
	v_cndmask_b32_e64 v68, v68, v69, s[40:41]
	v_cndmask_b32_e32 v69, 0, v231, vcc
	v_sub_f32_e32 v93, v68, v69
	v_pk_add_f32 v[68:69], v[72:73], v[92:93] neg_lo:[0,1] neg_hi:[0,1]
	ds_read_b128 v[70:73], v86 offset:1280
	ds_read_b128 v[88:91], v86 offset:1296
	v_pk_mul_f32 v[68:69], v[68:69], s[78:79] op_sel_hi:[1,0]
	s_waitcnt lgkmcnt(1)
; #define LAS __attribute__((address_space(3)))
; __device__ __forceinline__ void gla_gates(CP P, const bf16_t* PQ, int m0, int h, LAS unsigned char* lds) {
;     ...
;     for (int i = 0; i < 16; ++i) { const int t = tq * 16 + i; float z = b;
; #pragma unroll
;         for (int r4 = 0; r4 < 4; ++r4) { const f32x4 g4 = *(const LAS f32x4*)(gl + t * 32 + dir * 16 + r4 * 4);
;             z += g4[0] * w[r4 * 4] + g4[1] * w[r4 * 4 + 1] + g4[2] * w[r4 * 4 + 2] + g4[3] * w[r4 * 4 + 3]; }
;         c[i] = (fminf(z, 0.f) - __logf(1.0f + __expf(-fabsf(z)))) * (1.0f / 16.0f); }
	v_mov_b32_e32 v92, v70
	s_waitcnt lgkmcnt(0)
	v_mov_b32_e32 v93, v88
	v_mov_b32_e32 v88, v71
	v_pk_mul_f32 v[70:71], v[56:57], v[88:89]
	v_mov_b32_e32 v88, v72
	v_pk_fma_f32 v[70:71], v[50:51], v[92:93], v[70:71]
	v_mov_b32_e32 v89, v90
	v_pk_fma_f32 v[70:71], v[48:49], v[88:89], v[70:71]
	v_mov_b32_e32 v90, v73
	v_pk_fma_f32 v[70:71], v[44:45], v[90:91], v[70:71]
	s_nop 0
	v_add_f32_e32 v70, v85, v70
	v_add_f32_e32 v87, v70, v71
	ds_read_b128 v[70:73], v86 offset:1312
	ds_read_b128 v[88:91], v86 offset:1328
	s_waitcnt lgkmcnt(1)
	v_mov_b32_e32 v92, v70
	s_waitcnt lgkmcnt(0)
	v_mov_b32_e32 v93, v88
	v_mov_b32_e32 v88, v71
	v_pk_mul_f32 v[70:71], v[60:61], v[88:89]
	v_mov_b32_e32 v88, v72
	v_pk_fma_f32 v[70:71], v[58:59], v[92:93], v[70:71]
	v_mov_b32_e32 v89, v90
	v_pk_fma_f32 v[70:71], v[52:53], v[88:89], v[70:71]
	v_mov_b32_e32 v90, v73
	v_pk_fma_f32 v[70:71], v[46:47], v[90:91], v[70:71]
	s_nop 0
	v_add_f32_e32 v70, v87, v70
	v_add_f32_e32 v70, v70, v71
	v_min_f32_e32 v92, 0, v70
	v_mul_f32_e64 v70, |v70|, s33
	v_exp_f32_e32 v70, v70
	s_nop 0
	v_add_f32_e32 v70, 1.0, v70
	v_cmp_gt_f32_e32 vcc, s80, v70
	s_nop 1
	v_cndmask_b32_e64 v71, 0, 32, vcc
	v_ldexp_f32 v70, v70, v71
	v_log_f32_e32 v70, v70
	s_nop 0
	v_mul_f32_e32 v71, 0x3f317217, v70
	v_fma_f32 v71, v70, s92, -v71
	v_fmac_f32_e32 v71, 0x3377d1cf, v70
	v_fmac_f32_e32 v71, 0x3f317217, v70
	v_cmp_lt_f32_e64 s[40:41], |v70|, s93
	s_nop 1
	v_cndmask_b32_e64 v70, v70, v71, s[40:41]
	v_cndmask_b32_e32 v71, 0, v231, vcc
	v_sub_f32_e32 v94, v70, v71
	ds_read_b128 v[70:73], v86 offset:1408
	ds_read_b128 v[88:91], v86 offset:1424
	s_waitcnt lgkmcnt(1)
	v_mov_b32_e32 v96, v70
	s_waitcnt lgkmcnt(0)
	v_mov_b32_e32 v97, v88
	v_mov_b32_e32 v88, v71
	v_pk_mul_f32 v[70:71], v[56:57], v[88:89]
	v_mov_b32_e32 v88, v72
	v_pk_fma_f32 v[70:71], v[50:51], v[96:97], v[70:71]
	v_mov_b32_e32 v89, v90
	v_pk_fma_f32 v[70:71], v[48:49], v[88:89], v[70:71]
	v_mov_b32_e32 v90, v73
	v_pk_fma_f32 v[70:71], v[44:45], v[90:91], v[70:71]
	s_nop 0
	v_add_f32_e32 v70, v85, v70
	v_add_f32_e32 v87, v70, v71
	ds_read_b128 v[70:73], v86 offset:1440
	ds_read_b128 v[88:91], v86 offset:1456
	s_waitcnt lgkmcnt(1)
	v_mov_b32_e32 v96, v70
	s_waitcnt lgkmcnt(0)
	v_mov_b32_e32 v97, v88
	v_mov_b32_e32 v88, v71
	v_pk_mul_f32 v[70:71], v[60:61], v[88:89]
	v_mov_b32_e32 v88, v72
	v_pk_fma_f32 v[70:71], v[58:59], v[96:97], v[70:71]
	v_mov_b32_e32 v89, v90
	v_pk_fma_f32 v[70:71], v[52:53], v[88:89], v[70:71]
	v_mov_b32_e32 v90, v73
	v_pk_fma_f32 v[70:71], v[46:47], v[90:91], v[70:71]
	s_nop 0
	v_add_f32_e32 v70, v87, v70
	v_add_f32_e32 v70, v70, v71
	v_min_f32_e32 v93, 0, v70
	v_mul_f32_e64 v70, |v70|, s33
	v_exp_f32_e32 v70, v70
	s_nop 0
	v_add_f32_e32 v70, 1.0, v70
	v_cmp_gt_f32_e32 vcc, s80, v70
	s_nop 1
	v_cndmask_b32_e64 v71, 0, 32, vcc
	v_ldexp_f32 v70, v70, v71
	v_log_f32_e32 v70, v70
	s_nop 0
	v_mul_f32_e32 v71, 0x3f317217, v70
	v_fma_f32 v71, v70, s92, -v71
	v_fmac_f32_e32 v71, 0x3377d1cf, v70
	v_fmac_f32_e32 v71, 0x3f317217, v70
	v_cmp_lt_f32_e64 s[40:41], |v70|, s93
	s_nop 1
	v_cndmask_b32_e64 v70, v70, v71, s[40:41]
	v_cndmask_b32_e32 v71, 0, v231, vcc
	v_sub_f32_e32 v95, v70, v71
	v_pk_add_f32 v[70:71], v[92:93], v[94:95] neg_lo:[0,1] neg_hi:[0,1]
	ds_read_b128 v[88:91], v86 offset:1536
	ds_read_b128 v[92:95], v86 offset:1552
	v_pk_mul_f32 v[70:71], v[70:71], s[78:79] op_sel_hi:[1,0]
	s_waitcnt lgkmcnt(1)
	v_mov_b32_e32 v72, v88
	s_waitcnt lgkmcnt(0)
	v_mov_b32_e32 v73, v92
	v_mov_b32_e32 v92, v89
	v_pk_mul_f32 v[88:89], v[56:57], v[92:93]
	s_nop 0
	v_pk_fma_f32 v[72:73], v[50:51], v[72:73], v[88:89]
	v_mov_b32_e32 v88, v90
	v_mov_b32_e32 v89, v94
	v_pk_fma_f32 v[72:73], v[48:49], v[88:89], v[72:73]
	v_mov_b32_e32 v94, v91
	v_pk_fma_f32 v[72:73], v[44:45], v[94:95], v[72:73]
	ds_read_b128 v[88:91], v86 offset:1568
	ds_read_b128 v[92:95], v86 offset:1584
	v_add_f32_e32 v72, v85, v72
	v_add_f32_e32 v87, v72, v73
	s_waitcnt lgkmcnt(1)
	v_mov_b32_e32 v72, v88
	s_waitcnt lgkmcnt(0)
	v_mov_b32_e32 v73, v92
	v_mov_b32_e32 v92, v89
	v_pk_mul_f32 v[88:89], v[60:61], v[92:93]
	s_nop 0
	v_pk_fma_f32 v[72:73], v[58:59], v[72:73], v[88:89]
	v_mov_b32_e32 v88, v90
	v_mov_b32_e32 v89, v94
	v_pk_fma_f32 v[72:73], v[52:53], v[88:89], v[72:73]
	v_mov_b32_e32 v94, v91
	v_pk_fma_f32 v[72:73], v[46:47], v[94:95], v[72:73]
	ds_read_b128 v[88:91], v86 offset:1664
	ds_read_b128 v[92:95], v86 offset:1680
	v_add_f32_e32 v72, v87, v72
	v_add_f32_e32 v73, v72, v73
	v_min_f32_e32 v72, 0, v73
	v_mul_f32_e64 v73, |v73|, s33
	v_exp_f32_e32 v73, v73
	s_waitcnt lgkmcnt(0)
	v_mov_b32_e32 v99, v92
	v_mov_b32_e32 v92, v89
	v_mov_b32_e32 v98, v88
	v_add_f32_e32 v73, 1.0, v73
	v_cmp_gt_f32_e32 vcc, s80, v73
	v_pk_mul_f32 v[88:89], v[56:57], v[92:93]
	v_mov_b32_e32 v92, v90
	v_cndmask_b32_e64 v87, 0, 32, vcc
	v_ldexp_f32 v73, v73, v87
	v_log_f32_e32 v73, v73
	v_pk_fma_f32 v[88:89], v[50:51], v[98:99], v[88:89]
	v_mov_b32_e32 v93, v94
	v_pk_fma_f32 v[88:89], v[48:49], v[92:93], v[88:89]
	v_mul_f32_e32 v87, 0x3f317217, v73
	v_fma_f32 v87, v73, s92, -v87
	v_fmac_f32_e32 v87, 0x3377d1cf, v73
	v_fmac_f32_e32 v87, 0x3f317217, v73
	v_cmp_lt_f32_e64 s[40:41], |v73|, s93
	v_mov_b32_e32 v94, v91
	v_pk_fma_f32 v[88:89], v[44:45], v[94:95], v[88:89]
	v_cndmask_b32_e64 v73, v73, v87, s[40:41]
	v_cndmask_b32_e32 v87, 0, v231, vcc
	v_sub_f32_e32 v96, v73, v87
	v_add_f32_e32 v73, v85, v88
	v_add_f32_e32 v73, v73, v89
	ds_read_b128 v[88:91], v86 offset:1696
	ds_read_b128 v[92:95], v86 offset:1712
	s_waitcnt lgkmcnt(1)
; #define LAS __attribute__((address_space(3)))
; __device__ __forceinline__ void gla_gates(CP P, const bf16_t* PQ, int m0, int h, LAS unsigned char* lds) {
;     ...
;     for (int i = 0; i < 16; ++i) { const int t = tq * 16 + i; float z = b;
; #pragma unroll
;         for (int r4 = 0; r4 < 4; ++r4) { const f32x4 g4 = *(const LAS f32x4*)(gl + t * 32 + dir * 16 + r4 * 4);
;             z += g4[0] * w[r4 * 4] + g4[1] * w[r4 * 4 + 1] + g4[2] * w[r4 * 4 + 2] + g4[3] * w[r4 * 4 + 3]; }
;         c[i] = (fminf(z, 0.f) - __logf(1.0f + __expf(-fabsf(z)))) * (1.0f / 16.0f); }
;     if (dir == 0) {
; #pragma unroll
;         for (int i = 1; i < 16; ++i) c[i] += c[i - 1];
;         tot[(dir * 4 + tq) * 64 + d] = c[15]; }
;     else {
; #pragma unroll
;         for (int i = 14; i >= 0; --i) c[i] += c[i + 1];
;         tot[(dir * 4 + tq) * 64 + d] = c[0]; }
	v_mov_b32_e32 v98, v88
	s_waitcnt lgkmcnt(0)
	v_mov_b32_e32 v99, v92
	v_mov_b32_e32 v92, v89
	v_pk_mul_f32 v[88:89], v[60:61], v[92:93]
	v_mov_b32_e32 v92, v90
	v_pk_fma_f32 v[88:89], v[58:59], v[98:99], v[88:89]
	v_mov_b32_e32 v93, v94
	v_pk_fma_f32 v[88:89], v[52:53], v[92:93], v[88:89]
	v_mov_b32_e32 v94, v91
	v_pk_fma_f32 v[88:89], v[46:47], v[94:95], v[88:89]
	s_nop 0
	v_add_f32_e32 v73, v73, v88
	v_add_f32_e32 v87, v73, v89
	v_min_f32_e32 v73, 0, v87
	v_mul_f32_e64 v87, |v87|, s33
	v_exp_f32_e32 v87, v87
	s_nop 0
	v_add_f32_e32 v87, 1.0, v87
	v_cmp_gt_f32_e32 vcc, s80, v87
	s_nop 1
	v_cndmask_b32_e64 v88, 0, 32, vcc
	v_ldexp_f32 v87, v87, v88
	v_log_f32_e32 v87, v87
	s_nop 0
	v_mul_f32_e32 v88, 0x3f317217, v87
	v_fma_f32 v88, v87, s92, -v88
	v_fmac_f32_e32 v88, 0x3377d1cf, v87
	v_fmac_f32_e32 v88, 0x3f317217, v87
	v_cmp_lt_f32_e64 s[40:41], |v87|, s93
	s_nop 1
	v_cndmask_b32_e64 v87, v87, v88, s[40:41]
	v_cndmask_b32_e32 v88, 0, v231, vcc
	v_sub_f32_e32 v97, v87, v88
	ds_read_b128 v[88:91], v86 offset:1792
	ds_read_b128 v[92:95], v86 offset:1808
	v_pk_add_f32 v[72:73], v[72:73], v[96:97] neg_lo:[0,1] neg_hi:[0,1]
	s_waitcnt lgkmcnt(1)
	v_mov_b32_e32 v96, v88
	s_waitcnt lgkmcnt(0)
	v_mov_b32_e32 v97, v92
	v_mov_b32_e32 v92, v89
	v_pk_mul_f32 v[88:89], v[56:57], v[92:93]
	v_mov_b32_e32 v92, v90
	v_pk_fma_f32 v[88:89], v[50:51], v[96:97], v[88:89]
	v_mov_b32_e32 v93, v94
	v_pk_fma_f32 v[88:89], v[48:49], v[92:93], v[88:89]
	v_mov_b32_e32 v94, v91
	v_pk_fma_f32 v[88:89], v[44:45], v[94:95], v[88:89]
	v_pk_mul_f32 v[72:73], v[72:73], s[78:79] op_sel_hi:[1,0]
	v_add_f32_e32 v87, v85, v88
	v_add_f32_e32 v87, v87, v89
	ds_read_b128 v[88:91], v86 offset:1824
	ds_read_b128 v[92:95], v86 offset:1840
	s_waitcnt lgkmcnt(1)
	v_mov_b32_e32 v96, v88
	s_waitcnt lgkmcnt(0)
	v_mov_b32_e32 v97, v92
	v_mov_b32_e32 v92, v89
	v_pk_mul_f32 v[88:89], v[60:61], v[92:93]
	v_mov_b32_e32 v92, v90
	v_pk_fma_f32 v[88:89], v[58:59], v[96:97], v[88:89]
	v_mov_b32_e32 v93, v94
	v_pk_fma_f32 v[88:89], v[52:53], v[92:93], v[88:89]
	v_mov_b32_e32 v94, v91
	v_pk_fma_f32 v[88:89], v[46:47], v[94:95], v[88:89]
	s_nop 0
	v_add_f32_e32 v87, v87, v88
	v_add_f32_e32 v87, v87, v89
	v_min_f32_e32 v96, 0, v87
	v_mul_f32_e64 v87, |v87|, s33
	v_exp_f32_e32 v87, v87
	s_nop 0
	v_add_f32_e32 v87, 1.0, v87
	v_cmp_gt_f32_e32 vcc, s80, v87
	s_nop 1
	v_cndmask_b32_e64 v88, 0, 32, vcc
	v_ldexp_f32 v87, v87, v88
	v_log_f32_e32 v87, v87
	s_nop 0
	v_mul_f32_e32 v88, 0x3f317217, v87
	v_fma_f32 v88, v87, s92, -v88
	v_fmac_f32_e32 v88, 0x3377d1cf, v87
	v_fmac_f32_e32 v88, 0x3f317217, v87
	v_cmp_lt_f32_e64 s[40:41], |v87|, s93
	s_nop 1
	v_cndmask_b32_e64 v87, v87, v88, s[40:41]
	v_cndmask_b32_e32 v88, 0, v231, vcc
	v_sub_f32_e32 v98, v87, v88
	ds_read_b128 v[88:91], v86 offset:1920
	ds_read_b128 v[92:95], v86 offset:1936
	s_waitcnt lgkmcnt(1)
	v_mov_b32_e32 v100, v88
	s_waitcnt lgkmcnt(0)
	v_mov_b32_e32 v101, v92
	v_mov_b32_e32 v92, v89
	v_pk_mul_f32 v[56:57], v[56:57], v[92:93]
	s_nop 0
	v_pk_fma_f32 v[50:51], v[50:51], v[100:101], v[56:57]
	v_mov_b32_e32 v56, v90
	v_mov_b32_e32 v57, v94
	v_pk_fma_f32 v[48:49], v[48:49], v[56:57], v[50:51]
	v_mov_b32_e32 v94, v91
	v_pk_fma_f32 v[44:45], v[44:45], v[94:95], v[48:49]
	ds_read_b128 v[48:51], v86 offset:1952
	ds_read_b128 v[86:89], v86 offset:1968
	v_add_f32_e32 v44, v85, v44
	v_add_f32_e32 v56, v44, v45
	s_waitcnt lgkmcnt(1)
	v_mov_b32_e32 v44, v48
	s_waitcnt lgkmcnt(0)
	v_mov_b32_e32 v45, v86
	v_mov_b32_e32 v86, v49
	v_pk_mul_f32 v[48:49], v[60:61], v[86:87]
	s_nop 0
	v_pk_fma_f32 v[44:45], v[58:59], v[44:45], v[48:49]
	v_mov_b32_e32 v48, v50
	v_mov_b32_e32 v49, v88
	v_pk_fma_f32 v[44:45], v[52:53], v[48:49], v[44:45]
	v_mov_b32_e32 v88, v51
	v_pk_fma_f32 v[44:45], v[46:47], v[88:89], v[44:45]
	v_lshlrev_b32_e32 v46, 2, v81
	v_add_f32_e32 v44, v56, v44
	v_add_f32_e32 v44, v44, v45
	v_min_f32_e32 v97, 0, v44
	v_mul_f32_e64 v44, |v44|, s33
	v_exp_f32_e32 v44, v44
	s_nop 0
	v_add_f32_e32 v44, 1.0, v44
	v_cmp_gt_f32_e32 vcc, s80, v44
	s_nop 1
	v_cndmask_b32_e64 v45, 0, 32, vcc
	v_ldexp_f32 v44, v44, v45
	v_log_f32_e32 v44, v44
	s_nop 0
	v_mul_f32_e32 v45, 0x3f317217, v44
	v_fma_f32 v45, v44, s92, -v45
	v_fmac_f32_e32 v45, 0x3377d1cf, v44
	v_fmac_f32_e32 v45, 0x3f317217, v44
	v_cmp_lt_f32_e64 s[40:41], |v44|, s93
	s_nop 1
	v_cndmask_b32_e64 v44, v44, v45, s[40:41]
	v_cndmask_b32_e32 v45, 0, v231, vcc
	v_sub_f32_e32 v99, v44, v45
	v_pk_add_f32 v[44:45], v[96:97], v[98:99] neg_lo:[0,1] neg_hi:[0,1]
	v_cmp_gt_u32_e32 vcc, s10, v83
	s_movk_i32 s10, 0xff
	v_pk_mul_f32 v[44:45], v[44:45], s[78:79] op_sel_hi:[1,0]
	v_cmp_lt_u32_e64 s[40:41], s10, v83
	s_and_saveexec_b64 s[10:11], s[40:41]
	s_xor_b64 s[20:21], exec, s[10:11]
	s_cbranch_execz .LBB0_174
	v_add_f32_e32 v48, v44, v45
	v_add_f32_e32 v49, v73, v48
	v_add_f32_e32 v50, v72, v49
	v_add_f32_e32 v51, v71, v50
	v_add_f32_e32 v52, v70, v51
	v_add_f32_e32 v53, v69, v52
	v_add_f32_e32 v56, v68, v53
	v_add_f32_e32 v57, v67, v56
	v_add_f32_e32 v58, v66, v57
	v_add_f32_e32 v59, v65, v58
	v_add_f32_e32 v60, v64, v59
	v_add_f32_e32 v61, v63, v60
	v_add_f32_e32 v85, v62, v61
	v_add_f32_e32 v86, v55, v85
	v_lshl_add_u32 v44, v84, 2, 0
	v_lshlrev_b32_e32 v47, 8, v82
	v_add_f32_e32 v54, v54, v86
	v_add3_u32 v44, v44, v47, v46
	ds_write_b32 v44, v54 offset:8192

; #define LAS __attribute__((address_space(3)))
; __device__ __forceinline__ int otid() { int t = threadIdx.x; asm volatile("" : "+v"(t)); return t; }
; __device__ __forceinline__ float bflo(unsigned w) { return __uint_as_float(w << 16); }
; __device__ __forceinline__ float bfhi(unsigned w) { return __uint_as_float(w & 0xffff0000u); }
; __device__ __forceinline__ void lds_barrier() { asm volatile("s_waitcnt lgkmcnt(0)" ::: "memory"); __builtin_amdgcn_s_barrier(); asm volatile("" ::: "memory"); }
; __device__ __forceinline__ void gla_gates(CP P, const bf16_t* PQ, int m0, int h, LAS unsigned char* lds) {
;     ...
;     { const int idx = tid * 4, t = idx >> 5, r = idx & 31; const uint2 raw = *(const uint2*)(PQ + (size_t)(m0 + t) * 1792 + 1536 + r);
;         *(LAS f32x4*)(gl + idx) = (f32x4){bflo(raw.x), bfhi(raw.x), bflo(raw.y), bfhi(raw.y)}; }
;     float w[16];
; #pragma unroll
;     for (int r = 0; r < 16; ++r) w[r] = P->in[18][(dir * 16 + r) * 256 + h * 64 + d];
;     const float b = P->in[19][dir * 256 + h * 64 + d];
;     lds_barrier();
;     float c[16];
; #pragma unroll
;     for (int i = 0; i < 16; ++i) { const int t = tq * 16 + i; float z = b;
; #pragma unroll
;         for (int r4 = 0; r4 < 4; ++r4) { const f32x4 g4 = *(const LAS f32x4*)(gl + t * 32 + dir * 16 + r4 * 4);
;             z += g4[0] * w[r4 * 4] + g4[1] * w[r4 * 4 + 1] + g4[2] * w[r4 * 4 + 2] + g4[3] * w[r4 * 4 + 3]; }
; __device__ void gla_a_unit(CP P, int unit, LAS unsigned char* lds) {
;     const int c = unit & 127, h = (unit >> 7) & 3, b = unit >> 9, m0 = b * 8192 + c * 64;
;     const bf16_t* PQ = (const bf16_t*)(P->ws + OFF_PQ); bf16_t* GST = (bf16_t*)(P->ws + OFF_GST); float* GDEC = (float*)(P->ws + OFF_GDEC);
;     const int tid = otid(), lane = tid & 63, wid = tid >> 6;
;     const int t = tid >> 3, d8 = (tid & 7) * 8, v16 = (tid & 7) * 16;
;     const uint4 kraw = *(const uint4*)(PQ + (size_t)(m0 + t) * 1792 + 256 + h * 64 + d8);
;     const uint4 vr0 = *(const uint4*)(PQ + (size_t)(m0 + t) * 1792 + 512 + h * 128 + v16), vr1 = *(const uint4*)(PQ + (size_t)(m0 + t) * 1792 + 512 + h * 128 + v16 + 8);
;     gla_gates(P, PQ, m0, h, lds);
.LBB0_204:
	s_cmpk_gt_i32 s17, 0xfff
	s_cbranch_scc1 .LBB0_225
	s_and_b32 s18, s17, 0x7f
	s_ashr_i32 s11, s17, 9
	s_lshl_b32 s12, s11, 13
	s_lshl_b32 s13, s18, 6
	v_mov_b32_e32 v44, v191
	s_or_b32 s19, s12, s13
	s_bfe_u32 s10, s17, 0x20007
	v_ashrrev_i32_e32 v45, 3, v44
	v_add_u32_e32 v0, s19, v45
	v_mov_b64_e32 v[14:15], s[14:15]
	v_and_b32_e32 v46, 7, v44
	v_mad_i64_i32 v[0:1], s[12:13], v0, s81, v[14:15]
	s_lshl_b32 s66, s10, 7
	v_lshlrev_b32_e32 v12, 4, v46
	v_lshl_add_u64 v[2:3], v[0:1], 0, s[66:67]
	v_mov_b32_e32 v13, v184
	v_lshl_add_u64 v[2:3], v[2:3], 0, v[12:13]
	s_lshl_b32 s66, s10, 8
	v_mov_b64_e32 v[102:103], v[2:3]
	v_lshl_add_u64 v[0:1], v[0:1], 0, s[66:67]
	v_lshlrev_b32_e32 v2, 5, v46
	v_mov_b32_e32 v3, v184
	v_lshl_add_u64 v[4:5], v[0:1], 0, v[2:3]
	v_mov_b32_e32 v49, v191
	v_mov_b32_e32 v17, v184
	v_ashrrev_i32_e32 v16, 3, v49
	v_add_u32_e32 v16, s19, v16
	v_mad_i64_i32 v[14:15], s[20:21], v16, s81, v[14:15]
	v_lshlrev_b32_e32 v16, 3, v49
	v_and_b32_e32 v16, 56, v16
	v_lshl_add_u64 v[14:15], v[14:15], 0, v[16:17]
	global_load_dwordx2 v[16:17], v[14:15], off offset:3072
	s_load_dwordx4 s[20:23], s[0:1], 0x90
	v_ashrrev_i32_e32 v13, 8, v49
	v_lshl_add_u32 v18, v49, 4, 0
	s_lshl_b32 s12, s10, 6
	v_and_b32_e32 v47, 63, v49
	s_movk_i32 s13, 0x1000
	v_and_b32_e32 v50, 0xffffff00, v49
	s_waitcnt lgkmcnt(0)
	v_mov_b32_e32 v30, s22
	v_mov_b32_e32 v31, s23
	v_bfe_u32 v48, v49, 6, 2
	s_waitcnt vmcnt(0)
	v_lshlrev_b32_e32 v14, 16, v16
	v_and_b32_e32 v15, 0xffff0000, v16
	v_lshlrev_b32_e32 v16, 16, v17
	v_and_b32_e32 v17, 0xffff0000, v17
	ds_write_b128 v18, v[14:17]
	v_lshlrev_b32_e32 v16, 12, v13
	v_or3_b32 v16, v16, s12, v47
	v_mov_b32_e32 v14, s20
	v_mov_b32_e32 v15, s21
	v_ashrrev_i32_e32 v17, 31, v16
	v_lshl_add_u64 v[32:33], v[16:17], 2, v[14:15]
	v_add_co_u32_e32 v16, vcc, s13, v32
	s_movk_i32 s13, 0x3000
	s_nop 0
	v_addc_co_u32_e32 v17, vcc, 0, v33, vcc
	v_add_co_u32_e32 v34, vcc, s88, v32
	global_load_dword v20, v[32:33], off
	global_load_dword v24, v[32:33], off offset:1024
	global_load_dword v18, v[32:33], off offset:2048
	global_load_dword v14, v[32:33], off offset:3072
	v_addc_co_u32_e32 v35, vcc, 0, v33, vcc
	v_add_co_u32_e32 v32, vcc, s13, v32
	global_load_dword v21, v[34:35], off offset:-4096
	global_load_dword v25, v[16:17], off offset:1024
	global_load_dword v19, v[16:17], off offset:2048
	global_load_dword v15, v[16:17], off offset:3072
	global_load_dword v26, v[34:35], off
	global_load_dword v28, v[34:35], off offset:1024
	global_load_dword v22, v[34:35], off offset:2048
	s_nop 0
	global_load_dword v16, v[34:35], off offset:3072
	v_addc_co_u32_e32 v33, vcc, 0, v33, vcc
	global_load_dword v27, v[32:33], off
	global_load_dword v29, v[32:33], off offset:1024
	global_load_dword v23, v[32:33], off offset:2048
	global_load_dword v17, v[32:33], off offset:3072
	v_or3_b32 v32, v47, s12, v50
	v_ashrrev_i32_e32 v33, 31, v32
	v_lshl_add_u64 v[30:31], v[32:33], 2, v[30:31]
	global_load_dword v51, v[30:31], off
	global_load_dwordx4 v[8:11], v[102:103], off offset:512
	global_load_dwordx4 v[0:3], v[4:5], off offset:1040
	s_nop 0
	global_load_dwordx4 v[4:7], v[4:5], off offset:1024
	v_lshlrev_b32_e32 v30, 11, v48
	v_lshlrev_b32_e32 v31, 6, v13
	s_waitcnt lgkmcnt(0)
	s_barrier
	v_add3_u32 v52, 0, v30, v31
	ds_read_b128 v[30:33], v52
	ds_read_b128 v[34:37], v52 offset:16
	ds_read_b128 v[38:41], v52 offset:32
	ds_read_b128 v[54:57], v52 offset:48
	s_movk_i32 s12, 0x100
	s_waitcnt lgkmcnt(3)
	v_mov_b32_e32 v42, v30
	s_waitcnt lgkmcnt(2)
	v_mov_b32_e32 v43, v34
	v_mov_b32_e32 v34, v31
	s_waitcnt vmcnt(14)
	v_pk_mul_f32 v[30:31], v[24:25], v[34:35]
	s_nop 0
	v_pk_fma_f32 v[30:31], v[20:21], v[42:43], v[30:31]
	v_mov_b32_e32 v34, v32
	v_mov_b32_e32 v35, v36
	s_waitcnt vmcnt(13)
	v_pk_fma_f32 v[30:31], v[18:19], v[34:35], v[30:31]
	v_mov_b32_e32 v36, v33
	s_waitcnt vmcnt(12)
	v_pk_fma_f32 v[30:31], v[14:15], v[36:37], v[30:31]
	s_waitcnt vmcnt(3)
	v_add_f32_e32 v30, v51, v30
	v_add_f32_e32 v34, v30, v31
	s_waitcnt lgkmcnt(0)
	v_mov_b32_e32 v31, v54
	v_mov_b32_e32 v54, v39
	v_mov_b32_e32 v30, v38
	v_pk_mul_f32 v[32:33], v[28:29], v[54:55]
	s_nop 0
	v_pk_fma_f32 v[30:31], v[26:27], v[30:31], v[32:33]
	v_mov_b32_e32 v32, v40
	v_mov_b32_e32 v33, v56
	v_pk_fma_f32 v[30:31], v[22:23], v[32:33], v[30:31]
	v_mov_b32_e32 v56, v41
	v_pk_fma_f32 v[30:31], v[16:17], v[56:57], v[30:31]
	s_nop 0
	v_add_f32_e32 v30, v34, v30
	v_add_f32_e32 v30, v30, v31
	v_min_f32_e32 v38, 0, v30
	v_mul_f32_e64 v30, |v30|, s33
	v_exp_f32_e32 v30, v30
	s_nop 0
	v_add_f32_e32 v30, 1.0, v30
	v_cmp_gt_f32_e32 vcc, s80, v30
	s_nop 1
	v_cndmask_b32_e64 v31, 0, 32, vcc
	v_ldexp_f32 v30, v30, v31
	v_log_f32_e32 v30, v30
	s_nop 0
	v_mul_f32_e32 v31, 0x3f317217, v30
	v_fma_f32 v31, v30, s92, -v31
	v_fmac_f32_e32 v31, 0x3377d1cf, v30
	v_fmac_f32_e32 v31, 0x3f317217, v30
	v_cmp_lt_f32_e64 s[40:41], |v30|, s93
	s_nop 1
	v_cndmask_b32_e64 v30, v30, v31, s[40:41]
	v_cndmask_b32_e32 v31, 0, v231, vcc
	v_sub_f32_e32 v40, v30, v31
	ds_read_b128 v[30:33], v52 offset:128
	ds_read_b128 v[34:37], v52 offset:144
	s_waitcnt lgkmcnt(1)
	v_mov_b32_e32 v42, v30
	s_waitcnt lgkmcnt(0)
	v_mov_b32_e32 v43, v34
	v_mov_b32_e32 v34, v31
	v_pk_mul_f32 v[30:31], v[24:25], v[34:35]
	v_mov_b32_e32 v34, v32
	v_pk_fma_f32 v[30:31], v[20:21], v[42:43], v[30:31]
	v_mov_b32_e32 v35, v36
	v_pk_fma_f32 v[30:31], v[18:19], v[34:35], v[30:31]
	v_mov_b32_e32 v36, v33
	v_pk_fma_f32 v[30:31], v[14:15], v[36:37], v[30:31]
	s_nop 0
	v_add_f32_e32 v30, v51, v30
	v_add_f32_e32 v39, v30, v31
	ds_read_b128 v[30:33], v52 offset:160
	ds_read_b128 v[34:37], v52 offset:176
	s_waitcnt lgkmcnt(1)
	v_mov_b32_e32 v42, v30
	s_waitcnt lgkmcnt(0)
; #define LAS __attribute__((address_space(3)))
; __device__ __forceinline__ void gla_gates(CP P, const bf16_t* PQ, int m0, int h, LAS unsigned char* lds) {
;     ...
;     for (int i = 0; i < 16; ++i) { const int t = tq * 16 + i; float z = b;
; #pragma unroll
;         for (int r4 = 0; r4 < 4; ++r4) { const f32x4 g4 = *(const LAS f32x4*)(gl + t * 32 + dir * 16 + r4 * 4);
;             z += g4[0] * w[r4 * 4] + g4[1] * w[r4 * 4 + 1] + g4[2] * w[r4 * 4 + 2] + g4[3] * w[r4 * 4 + 3]; }
;         c[i] = (fminf(z, 0.f) - __logf(1.0f + __expf(-fabsf(z)))) * (1.0f / 16.0f); }
	v_mov_b32_e32 v43, v34
	v_mov_b32_e32 v34, v31
	v_pk_mul_f32 v[30:31], v[28:29], v[34:35]
	v_mov_b32_e32 v34, v32
	v_pk_fma_f32 v[30:31], v[26:27], v[42:43], v[30:31]
	v_mov_b32_e32 v35, v36
	v_pk_fma_f32 v[30:31], v[22:23], v[34:35], v[30:31]
	v_mov_b32_e32 v36, v33
	v_pk_fma_f32 v[30:31], v[16:17], v[36:37], v[30:31]
	s_nop 0
	v_add_f32_e32 v30, v39, v30
	v_add_f32_e32 v30, v30, v31
	v_min_f32_e32 v39, 0, v30
	v_mul_f32_e64 v30, |v30|, s33
	v_exp_f32_e32 v30, v30
	s_nop 0
	v_add_f32_e32 v30, 1.0, v30
	v_cmp_gt_f32_e32 vcc, s80, v30
	s_nop 1
	v_cndmask_b32_e64 v31, 0, 32, vcc
	v_ldexp_f32 v30, v30, v31
	v_log_f32_e32 v30, v30
	s_nop 0
	v_mul_f32_e32 v31, 0x3f317217, v30
	v_fma_f32 v31, v30, s92, -v31
	v_fmac_f32_e32 v31, 0x3377d1cf, v30
	v_fmac_f32_e32 v31, 0x3f317217, v30
	v_cmp_lt_f32_e64 s[40:41], |v30|, s93
	s_nop 1
	v_cndmask_b32_e64 v30, v30, v31, s[40:41]
	v_cndmask_b32_e32 v31, 0, v231, vcc
	v_sub_f32_e32 v41, v30, v31
	v_pk_add_f32 v[30:31], v[38:39], v[40:41] neg_lo:[0,1] neg_hi:[0,1]
	ds_read_b128 v[32:35], v52 offset:256
	ds_read_b128 v[36:39], v52 offset:272
	v_pk_mul_f32 v[30:31], v[30:31], s[78:79] op_sel_hi:[1,0]
	s_waitcnt lgkmcnt(1)
	v_mov_b32_e32 v40, v32
	s_waitcnt lgkmcnt(0)
	v_mov_b32_e32 v41, v36
	v_mov_b32_e32 v36, v33
	v_pk_mul_f32 v[32:33], v[24:25], v[36:37]
	v_mov_b32_e32 v36, v34
	v_pk_fma_f32 v[32:33], v[20:21], v[40:41], v[32:33]
	v_mov_b32_e32 v37, v38
	v_pk_fma_f32 v[32:33], v[18:19], v[36:37], v[32:33]
	v_mov_b32_e32 v38, v35
	v_pk_fma_f32 v[32:33], v[14:15], v[38:39], v[32:33]
	s_nop 0
	v_add_f32_e32 v32, v51, v32
	v_add_f32_e32 v42, v32, v33
	ds_read_b128 v[32:35], v52 offset:288
	ds_read_b128 v[36:39], v52 offset:304
	s_waitcnt lgkmcnt(1)
	v_mov_b32_e32 v40, v32
	s_waitcnt lgkmcnt(0)
	v_mov_b32_e32 v41, v36
	v_mov_b32_e32 v36, v33
	v_pk_mul_f32 v[32:33], v[28:29], v[36:37]
	v_mov_b32_e32 v36, v34
	v_pk_fma_f32 v[32:33], v[26:27], v[40:41], v[32:33]
	v_mov_b32_e32 v37, v38
	v_pk_fma_f32 v[32:33], v[22:23], v[36:37], v[32:33]
	v_mov_b32_e32 v38, v35
	v_pk_fma_f32 v[32:33], v[16:17], v[38:39], v[32:33]
	s_nop 0
	v_add_f32_e32 v32, v42, v32
	v_add_f32_e32 v32, v32, v33
	v_min_f32_e32 v40, 0, v32
	v_mul_f32_e64 v32, |v32|, s33
	v_exp_f32_e32 v32, v32
	s_nop 0
	v_add_f32_e32 v32, 1.0, v32
	v_cmp_gt_f32_e32 vcc, s80, v32
	s_nop 1
	v_cndmask_b32_e64 v33, 0, 32, vcc
	v_ldexp_f32 v32, v32, v33
	v_log_f32_e32 v32, v32
	s_nop 0
	v_mul_f32_e32 v33, 0x3f317217, v32
	v_fma_f32 v33, v32, s92, -v33
	v_fmac_f32_e32 v33, 0x3377d1cf, v32
	v_fmac_f32_e32 v33, 0x3f317217, v32
	v_cmp_lt_f32_e64 s[40:41], |v32|, s93
	s_nop 1
	v_cndmask_b32_e64 v32, v32, v33, s[40:41]
	v_cndmask_b32_e32 v33, 0, v231, vcc
	v_sub_f32_e32 v42, v32, v33
	ds_read_b128 v[32:35], v52 offset:384
	ds_read_b128 v[36:39], v52 offset:400
	s_waitcnt lgkmcnt(1)
	v_mov_b32_e32 v54, v32
	s_waitcnt lgkmcnt(0)
	v_mov_b32_e32 v55, v36
	v_mov_b32_e32 v36, v33
	v_pk_mul_f32 v[32:33], v[24:25], v[36:37]
	v_mov_b32_e32 v36, v34
	v_pk_fma_f32 v[32:33], v[20:21], v[54:55], v[32:33]
	v_mov_b32_e32 v37, v38
	v_pk_fma_f32 v[32:33], v[18:19], v[36:37], v[32:33]
	v_mov_b32_e32 v38, v35
	v_pk_fma_f32 v[32:33], v[14:15], v[38:39], v[32:33]
	s_nop 0
	v_add_f32_e32 v32, v51, v32
	v_add_f32_e32 v41, v32, v33
	ds_read_b128 v[32:35], v52 offset:416
	ds_read_b128 v[36:39], v52 offset:432
	s_waitcnt lgkmcnt(1)
	v_mov_b32_e32 v54, v32
	s_waitcnt lgkmcnt(0)
	v_mov_b32_e32 v55, v36
	v_mov_b32_e32 v36, v33
	v_pk_mul_f32 v[32:33], v[28:29], v[36:37]
	v_mov_b32_e32 v36, v34
	v_pk_fma_f32 v[32:33], v[26:27], v[54:55], v[32:33]
	v_mov_b32_e32 v37, v38
	v_pk_fma_f32 v[32:33], v[22:23], v[36:37], v[32:33]
	v_mov_b32_e32 v38, v35
	v_pk_fma_f32 v[32:33], v[16:17], v[38:39], v[32:33]
	s_nop 0
	v_add_f32_e32 v32, v41, v32
	v_add_f32_e32 v32, v32, v33
	v_min_f32_e32 v41, 0, v32
	v_mul_f32_e64 v32, |v32|, s33
	v_exp_f32_e32 v32, v32
	s_nop 0
	v_add_f32_e32 v32, 1.0, v32
	v_cmp_gt_f32_e32 vcc, s80, v32
	s_nop 1
	v_cndmask_b32_e64 v33, 0, 32, vcc
	v_ldexp_f32 v32, v32, v33
	v_log_f32_e32 v32, v32
	s_nop 0
	v_mul_f32_e32 v33, 0x3f317217, v32
	v_fma_f32 v33, v32, s92, -v33
	v_fmac_f32_e32 v33, 0x3377d1cf, v32
	v_fmac_f32_e32 v33, 0x3f317217, v32
	v_cmp_lt_f32_e64 s[40:41], |v32|, s93
	s_nop 1
	v_cndmask_b32_e64 v32, v32, v33, s[40:41]
	v_cndmask_b32_e32 v33, 0, v231, vcc
	v_sub_f32_e32 v43, v32, v33
	v_pk_add_f32 v[32:33], v[40:41], v[42:43] neg_lo:[0,1] neg_hi:[0,1]
	ds_read_b128 v[34:37], v52 offset:512
	ds_read_b128 v[38:41], v52 offset:528
	v_pk_mul_f32 v[32:33], v[32:33], s[78:79] op_sel_hi:[1,0]
	s_waitcnt lgkmcnt(1)
	v_mov_b32_e32 v42, v34
	s_waitcnt lgkmcnt(0)
	v_mov_b32_e32 v43, v38
	v_mov_b32_e32 v38, v35
	v_pk_mul_f32 v[34:35], v[24:25], v[38:39]
	v_mov_b32_e32 v38, v36
	v_pk_fma_f32 v[34:35], v[20:21], v[42:43], v[34:35]
	v_mov_b32_e32 v39, v40
	v_pk_fma_f32 v[34:35], v[18:19], v[38:39], v[34:35]
	v_mov_b32_e32 v40, v37
	v_pk_fma_f32 v[34:35], v[14:15], v[40:41], v[34:35]
	s_nop 0
	v_add_f32_e32 v34, v51, v34
	v_add_f32_e32 v53, v34, v35
	ds_read_b128 v[34:37], v52 offset:544
	ds_read_b128 v[38:41], v52 offset:560
	s_waitcnt lgkmcnt(1)
	v_mov_b32_e32 v42, v34
	s_waitcnt lgkmcnt(0)
; #define LAS __attribute__((address_space(3)))
; __device__ __forceinline__ void gla_gates(CP P, const bf16_t* PQ, int m0, int h, LAS unsigned char* lds) {
;     ...
;     for (int i = 0; i < 16; ++i) { const int t = tq * 16 + i; float z = b;
; #pragma unroll
;         for (int r4 = 0; r4 < 4; ++r4) { const f32x4 g4 = *(const LAS f32x4*)(gl + t * 32 + dir * 16 + r4 * 4);
;             z += g4[0] * w[r4 * 4] + g4[1] * w[r4 * 4 + 1] + g4[2] * w[r4 * 4 + 2] + g4[3] * w[r4 * 4 + 3]; }
;         c[i] = (fminf(z, 0.f) - __logf(1.0f + __expf(-fabsf(z)))) * (1.0f / 16.0f); }
	v_mov_b32_e32 v43, v38
	v_mov_b32_e32 v38, v35
	v_pk_mul_f32 v[34:35], v[28:29], v[38:39]
	v_mov_b32_e32 v38, v36
	v_pk_fma_f32 v[34:35], v[26:27], v[42:43], v[34:35]
	v_mov_b32_e32 v39, v40
	v_pk_fma_f32 v[34:35], v[22:23], v[38:39], v[34:35]
	v_mov_b32_e32 v40, v37
	v_pk_fma_f32 v[34:35], v[16:17], v[40:41], v[34:35]
	s_nop 0
	v_add_f32_e32 v34, v53, v34
	v_add_f32_e32 v34, v34, v35
	v_min_f32_e32 v42, 0, v34
	v_mul_f32_e64 v34, |v34|, s33
	v_exp_f32_e32 v34, v34
	s_nop 0
	v_add_f32_e32 v34, 1.0, v34
	v_cmp_gt_f32_e32 vcc, s80, v34
	s_nop 1
	v_cndmask_b32_e64 v35, 0, 32, vcc
	v_ldexp_f32 v34, v34, v35
	v_log_f32_e32 v34, v34
	s_nop 0
	v_mul_f32_e32 v35, 0x3f317217, v34
	v_fma_f32 v35, v34, s92, -v35
	v_fmac_f32_e32 v35, 0x3377d1cf, v34
	v_fmac_f32_e32 v35, 0x3f317217, v34
	v_cmp_lt_f32_e64 s[40:41], |v34|, s93
	s_nop 1
	v_cndmask_b32_e64 v34, v34, v35, s[40:41]
	v_cndmask_b32_e32 v35, 0, v231, vcc
	v_sub_f32_e32 v54, v34, v35
	ds_read_b128 v[34:37], v52 offset:640
	ds_read_b128 v[38:41], v52 offset:656
	s_waitcnt lgkmcnt(1)
	v_mov_b32_e32 v56, v34
	s_waitcnt lgkmcnt(0)
	v_mov_b32_e32 v57, v38
	v_mov_b32_e32 v38, v35
	v_pk_mul_f32 v[34:35], v[24:25], v[38:39]
	v_mov_b32_e32 v38, v36
	v_pk_fma_f32 v[34:35], v[20:21], v[56:57], v[34:35]
	v_mov_b32_e32 v39, v40
	v_pk_fma_f32 v[34:35], v[18:19], v[38:39], v[34:35]
	v_mov_b32_e32 v40, v37
	v_pk_fma_f32 v[34:35], v[14:15], v[40:41], v[34:35]
	s_nop 0
	v_add_f32_e32 v34, v51, v34
	v_add_f32_e32 v43, v34, v35
	ds_read_b128 v[34:37], v52 offset:672
	ds_read_b128 v[38:41], v52 offset:688
	s_waitcnt lgkmcnt(1)
	v_mov_b32_e32 v56, v34
	s_waitcnt lgkmcnt(0)
	v_mov_b32_e32 v57, v38
	v_mov_b32_e32 v38, v35
	v_pk_mul_f32 v[34:35], v[28:29], v[38:39]
	v_mov_b32_e32 v38, v36
	v_pk_fma_f32 v[34:35], v[26:27], v[56:57], v[34:35]
	v_mov_b32_e32 v39, v40
	v_pk_fma_f32 v[34:35], v[22:23], v[38:39], v[34:35]
	v_mov_b32_e32 v40, v37
	v_pk_fma_f32 v[34:35], v[16:17], v[40:41], v[34:35]
	s_nop 0
	v_add_f32_e32 v34, v43, v34
	v_add_f32_e32 v34, v34, v35
	v_min_f32_e32 v43, 0, v34
	v_mul_f32_e64 v34, |v34|, s33
	v_exp_f32_e32 v34, v34
	s_nop 0
	v_add_f32_e32 v34, 1.0, v34
	v_cmp_gt_f32_e32 vcc, s80, v34
	s_nop 1
	v_cndmask_b32_e64 v35, 0, 32, vcc
	v_ldexp_f32 v34, v34, v35
	v_log_f32_e32 v34, v34
	s_nop 0
	v_mul_f32_e32 v35, 0x3f317217, v34
	v_fma_f32 v35, v34, s92, -v35
	v_fmac_f32_e32 v35, 0x3377d1cf, v34
	v_fmac_f32_e32 v35, 0x3f317217, v34
	v_cmp_lt_f32_e64 s[40:41], |v34|, s93
	s_nop 1
	v_cndmask_b32_e64 v34, v34, v35, s[40:41]
	v_cndmask_b32_e32 v35, 0, v231, vcc
	v_sub_f32_e32 v55, v34, v35
	v_pk_add_f32 v[34:35], v[42:43], v[54:55] neg_lo:[0,1] neg_hi:[0,1]
	ds_read_b128 v[36:39], v52 offset:768
	ds_read_b128 v[40:43], v52 offset:784
	v_pk_mul_f32 v[34:35], v[34:35], s[78:79] op_sel_hi:[1,0]
	s_waitcnt lgkmcnt(1)
	v_mov_b32_e32 v54, v36
	s_waitcnt lgkmcnt(0)
	v_mov_b32_e32 v55, v40
	v_mov_b32_e32 v40, v37
	v_pk_mul_f32 v[36:37], v[24:25], v[40:41]
	v_mov_b32_e32 v40, v38
	v_pk_fma_f32 v[36:37], v[20:21], v[54:55], v[36:37]
	v_mov_b32_e32 v41, v42
	v_pk_fma_f32 v[36:37], v[18:19], v[40:41], v[36:37]
	v_mov_b32_e32 v42, v39
	v_pk_fma_f32 v[36:37], v[14:15], v[42:43], v[36:37]
	s_nop 0
	v_add_f32_e32 v36, v51, v36
	v_add_f32_e32 v53, v36, v37
	ds_read_b128 v[36:39], v52 offset:800
	ds_read_b128 v[40:43], v52 offset:816
	s_waitcnt lgkmcnt(1)
	v_mov_b32_e32 v54, v36
	s_waitcnt lgkmcnt(0)
	v_mov_b32_e32 v55, v40
	v_mov_b32_e32 v40, v37
	v_pk_mul_f32 v[36:37], v[28:29], v[40:41]
	v_mov_b32_e32 v40, v38
	v_pk_fma_f32 v[36:37], v[26:27], v[54:55], v[36:37]
	v_mov_b32_e32 v41, v42
	v_pk_fma_f32 v[36:37], v[22:23], v[40:41], v[36:37]
	v_mov_b32_e32 v42, v39
	v_pk_fma_f32 v[36:37], v[16:17], v[42:43], v[36:37]
	s_nop 0
	v_add_f32_e32 v36, v53, v36
	v_add_f32_e32 v36, v36, v37
	v_min_f32_e32 v54, 0, v36
	v_mul_f32_e64 v36, |v36|, s33
	v_exp_f32_e32 v36, v36
	s_nop 0
	v_add_f32_e32 v36, 1.0, v36
	v_cmp_gt_f32_e32 vcc, s80, v36
	s_nop 1
	v_cndmask_b32_e64 v37, 0, 32, vcc
	v_ldexp_f32 v36, v36, v37
	v_log_f32_e32 v36, v36
	s_nop 0
	v_mul_f32_e32 v37, 0x3f317217, v36
	v_fma_f32 v37, v36, s92, -v37
	v_fmac_f32_e32 v37, 0x3377d1cf, v36
	v_fmac_f32_e32 v37, 0x3f317217, v36
	v_cmp_lt_f32_e64 s[40:41], |v36|, s93
	s_nop 1
	v_cndmask_b32_e64 v36, v36, v37, s[40:41]
	v_cndmask_b32_e32 v37, 0, v231, vcc
	v_sub_f32_e32 v56, v36, v37
	ds_read_b128 v[36:39], v52 offset:896
	ds_read_b128 v[40:43], v52 offset:912
	s_waitcnt lgkmcnt(1)
	v_mov_b32_e32 v58, v36
	s_waitcnt lgkmcnt(0)
	v_mov_b32_e32 v59, v40
	v_mov_b32_e32 v40, v37
	v_pk_mul_f32 v[36:37], v[24:25], v[40:41]
	v_mov_b32_e32 v40, v38
	v_pk_fma_f32 v[36:37], v[20:21], v[58:59], v[36:37]
	v_mov_b32_e32 v41, v42
	v_pk_fma_f32 v[36:37], v[18:19], v[40:41], v[36:37]
	v_mov_b32_e32 v42, v39
	v_pk_fma_f32 v[36:37], v[14:15], v[42:43], v[36:37]
	s_nop 0
	v_add_f32_e32 v36, v51, v36
	v_add_f32_e32 v53, v36, v37
	ds_read_b128 v[36:39], v52 offset:928
	ds_read_b128 v[40:43], v52 offset:944
	s_waitcnt lgkmcnt(1)
	v_mov_b32_e32 v58, v36
	s_waitcnt lgkmcnt(0)
	v_mov_b32_e32 v59, v40
	v_mov_b32_e32 v40, v37
	v_pk_mul_f32 v[36:37], v[28:29], v[40:41]
	v_mov_b32_e32 v40, v38
	v_pk_fma_f32 v[36:37], v[26:27], v[58:59], v[36:37]
	v_mov_b32_e32 v41, v42
	v_pk_fma_f32 v[36:37], v[22:23], v[40:41], v[36:37]
	v_mov_b32_e32 v42, v39
	v_pk_fma_f32 v[36:37], v[16:17], v[42:43], v[36:37]
	s_nop 0
	v_add_f32_e32 v36, v53, v36
	v_add_f32_e32 v36, v36, v37
	v_min_f32_e32 v55, 0, v36
	v_mul_f32_e64 v36, |v36|, s33
	v_exp_f32_e32 v36, v36
	s_nop 0
	v_add_f32_e32 v36, 1.0, v36
	v_cmp_gt_f32_e32 vcc, s80, v36
	s_nop 1
	v_cndmask_b32_e64 v37, 0, 32, vcc
	v_ldexp_f32 v36, v36, v37
	v_log_f32_e32 v36, v36
	s_nop 0
	v_mul_f32_e32 v37, 0x3f317217, v36
	v_fma_f32 v37, v36, s92, -v37
	v_fmac_f32_e32 v37, 0x3377d1cf, v36
	v_fmac_f32_e32 v37, 0x3f317217, v36
	v_cmp_lt_f32_e64 s[40:41], |v36|, s93
	s_nop 1
	v_cndmask_b32_e64 v36, v36, v37, s[40:41]
	v_cndmask_b32_e32 v37, 0, v231, vcc
	v_sub_f32_e32 v57, v36, v37
	v_pk_add_f32 v[36:37], v[54:55], v[56:57] neg_lo:[0,1] neg_hi:[0,1]
	ds_read_b128 v[38:41], v52 offset:1024
	ds_read_b128 v[54:57], v52 offset:1040
	v_pk_mul_f32 v[36:37], v[36:37], s[78:79] op_sel_hi:[1,0]
	s_waitcnt lgkmcnt(1)
; #define LAS __attribute__((address_space(3)))
; __device__ __forceinline__ void gla_gates(CP P, const bf16_t* PQ, int m0, int h, LAS unsigned char* lds) {
;     ...
;     for (int i = 0; i < 16; ++i) { const int t = tq * 16 + i; float z = b;
; #pragma unroll
;         for (int r4 = 0; r4 < 4; ++r4) { const f32x4 g4 = *(const LAS f32x4*)(gl + t * 32 + dir * 16 + r4 * 4);
;             z += g4[0] * w[r4 * 4] + g4[1] * w[r4 * 4 + 1] + g4[2] * w[r4 * 4 + 2] + g4[3] * w[r4 * 4 + 3]; }
;         c[i] = (fminf(z, 0.f) - __logf(1.0f + __expf(-fabsf(z)))) * (1.0f / 16.0f); }
	v_mov_b32_e32 v42, v38
	s_waitcnt lgkmcnt(0)
	v_mov_b32_e32 v43, v54
	v_mov_b32_e32 v54, v39
	v_pk_mul_f32 v[38:39], v[24:25], v[54:55]
	s_nop 0
	v_pk_fma_f32 v[38:39], v[20:21], v[42:43], v[38:39]
	v_mov_b32_e32 v42, v40
	v_mov_b32_e32 v43, v56
	v_pk_fma_f32 v[38:39], v[18:19], v[42:43], v[38:39]
	v_mov_b32_e32 v56, v41
	v_pk_fma_f32 v[38:39], v[14:15], v[56:57], v[38:39]
	s_nop 0
	v_add_f32_e32 v38, v51, v38
	v_add_f32_e32 v53, v38, v39
	ds_read_b128 v[38:41], v52 offset:1056
	ds_read_b128 v[54:57], v52 offset:1072
	s_waitcnt lgkmcnt(1)
	v_mov_b32_e32 v42, v38
	s_waitcnt lgkmcnt(0)
	v_mov_b32_e32 v43, v54
	v_mov_b32_e32 v54, v39
	v_pk_mul_f32 v[38:39], v[28:29], v[54:55]
	s_nop 0
	v_pk_fma_f32 v[38:39], v[26:27], v[42:43], v[38:39]
	v_mov_b32_e32 v42, v40
	v_mov_b32_e32 v43, v56
	v_pk_fma_f32 v[38:39], v[22:23], v[42:43], v[38:39]
	v_mov_b32_e32 v56, v41
	v_pk_fma_f32 v[38:39], v[16:17], v[56:57], v[38:39]
	s_nop 0
	v_add_f32_e32 v38, v53, v38
	v_add_f32_e32 v38, v38, v39
	v_min_f32_e32 v42, 0, v38
	v_mul_f32_e64 v38, |v38|, s33
	v_exp_f32_e32 v38, v38
	s_nop 0
	v_add_f32_e32 v38, 1.0, v38
	v_cmp_gt_f32_e32 vcc, s80, v38
	s_nop 1
	v_cndmask_b32_e64 v39, 0, 32, vcc
	v_ldexp_f32 v38, v38, v39
	v_log_f32_e32 v38, v38
	s_nop 0
	v_mul_f32_e32 v39, 0x3f317217, v38
	v_fma_f32 v39, v38, s92, -v39
	v_fmac_f32_e32 v39, 0x3377d1cf, v38
	v_fmac_f32_e32 v39, 0x3f317217, v38
	v_cmp_lt_f32_e64 s[40:41], |v38|, s93
	s_nop 1
	v_cndmask_b32_e64 v38, v38, v39, s[40:41]
	v_cndmask_b32_e32 v39, 0, v231, vcc
	v_sub_f32_e32 v58, v38, v39
	ds_read_b128 v[38:41], v52 offset:1152
	ds_read_b128 v[54:57], v52 offset:1168
	s_waitcnt lgkmcnt(1)
	v_mov_b32_e32 v60, v38
	s_waitcnt lgkmcnt(0)
	v_mov_b32_e32 v61, v54
	v_mov_b32_e32 v54, v39
	v_pk_mul_f32 v[38:39], v[24:25], v[54:55]
	v_mov_b32_e32 v54, v40
	v_pk_fma_f32 v[38:39], v[20:21], v[60:61], v[38:39]
	v_mov_b32_e32 v55, v56
	v_pk_fma_f32 v[38:39], v[18:19], v[54:55], v[38:39]
	v_mov_b32_e32 v56, v41
	v_pk_fma_f32 v[38:39], v[14:15], v[56:57], v[38:39]
	s_nop 0
	v_add_f32_e32 v38, v51, v38
	v_add_f32_e32 v43, v38, v39
	ds_read_b128 v[38:41], v52 offset:1184
	ds_read_b128 v[54:57], v52 offset:1200
	s_waitcnt lgkmcnt(1)
	v_mov_b32_e32 v60, v38
	s_waitcnt lgkmcnt(0)
	v_mov_b32_e32 v61, v54
	v_mov_b32_e32 v54, v39
	v_pk_mul_f32 v[38:39], v[28:29], v[54:55]
	v_mov_b32_e32 v54, v40
	v_pk_fma_f32 v[38:39], v[26:27], v[60:61], v[38:39]
	v_mov_b32_e32 v55, v56
	v_pk_fma_f32 v[38:39], v[22:23], v[54:55], v[38:39]
	v_mov_b32_e32 v56, v41
	v_pk_fma_f32 v[38:39], v[16:17], v[56:57], v[38:39]
	s_nop 0
	v_add_f32_e32 v38, v43, v38
	v_add_f32_e32 v38, v38, v39
	v_min_f32_e32 v43, 0, v38
	v_mul_f32_e64 v38, |v38|, s33
	v_exp_f32_e32 v38, v38
	s_nop 0
	v_add_f32_e32 v38, 1.0, v38
	v_cmp_gt_f32_e32 vcc, s80, v38
	s_nop 1
	v_cndmask_b32_e64 v39, 0, 32, vcc
	v_ldexp_f32 v38, v38, v39
	v_log_f32_e32 v38, v38
	s_nop 0
	v_mul_f32_e32 v39, 0x3f317217, v38
	v_fma_f32 v39, v38, s92, -v39
	v_fmac_f32_e32 v39, 0x3377d1cf, v38
	v_fmac_f32_e32 v39, 0x3f317217, v38
	v_cmp_lt_f32_e64 s[40:41], |v38|, s93
	s_nop 1
	v_cndmask_b32_e64 v38, v38, v39, s[40:41]
	v_cndmask_b32_e32 v39, 0, v231, vcc
	v_sub_f32_e32 v59, v38, v39
	v_pk_add_f32 v[38:39], v[42:43], v[58:59] neg_lo:[0,1] neg_hi:[0,1]
	ds_read_b128 v[40:43], v52 offset:1280
	ds_read_b128 v[54:57], v52 offset:1296
	v_pk_mul_f32 v[38:39], v[38:39], s[78:79] op_sel_hi:[1,0]
	s_waitcnt lgkmcnt(1)
	v_mov_b32_e32 v58, v40
	s_waitcnt lgkmcnt(0)
	v_mov_b32_e32 v59, v54
	v_mov_b32_e32 v54, v41
	v_pk_mul_f32 v[40:41], v[24:25], v[54:55]
	v_mov_b32_e32 v54, v42
	v_pk_fma_f32 v[40:41], v[20:21], v[58:59], v[40:41]
	v_mov_b32_e32 v55, v56
	v_pk_fma_f32 v[40:41], v[18:19], v[54:55], v[40:41]
	v_mov_b32_e32 v56, v43
	v_pk_fma_f32 v[40:41], v[14:15], v[56:57], v[40:41]
	s_nop 0
	v_add_f32_e32 v40, v51, v40
	v_add_f32_e32 v53, v40, v41
	ds_read_b128 v[40:43], v52 offset:1312
	ds_read_b128 v[54:57], v52 offset:1328
	s_waitcnt lgkmcnt(1)
	v_mov_b32_e32 v58, v40
	s_waitcnt lgkmcnt(0)
	v_mov_b32_e32 v59, v54
	v_mov_b32_e32 v54, v41
	v_pk_mul_f32 v[40:41], v[28:29], v[54:55]
	v_mov_b32_e32 v54, v42
	v_pk_fma_f32 v[40:41], v[26:27], v[58:59], v[40:41]
	v_mov_b32_e32 v55, v56
	v_pk_fma_f32 v[40:41], v[22:23], v[54:55], v[40:41]
	v_mov_b32_e32 v56, v43
	v_pk_fma_f32 v[40:41], v[16:17], v[56:57], v[40:41]
	s_nop 0
	v_add_f32_e32 v40, v53, v40
	v_add_f32_e32 v40, v40, v41
	v_min_f32_e32 v58, 0, v40
	v_mul_f32_e64 v40, |v40|, s33
	v_exp_f32_e32 v40, v40
	s_nop 0
	v_add_f32_e32 v40, 1.0, v40
	v_cmp_gt_f32_e32 vcc, s80, v40
	s_nop 1
	v_cndmask_b32_e64 v41, 0, 32, vcc
	v_ldexp_f32 v40, v40, v41
	v_log_f32_e32 v40, v40
	s_nop 0
	v_mul_f32_e32 v41, 0x3f317217, v40
	v_fma_f32 v41, v40, s92, -v41
	v_fmac_f32_e32 v41, 0x3377d1cf, v40
	v_fmac_f32_e32 v41, 0x3f317217, v40
	v_cmp_lt_f32_e64 s[40:41], |v40|, s93
	s_nop 1
	v_cndmask_b32_e64 v40, v40, v41, s[40:41]
	v_cndmask_b32_e32 v41, 0, v231, vcc
	v_sub_f32_e32 v60, v40, v41
	ds_read_b128 v[40:43], v52 offset:1408
	ds_read_b128 v[54:57], v52 offset:1424
	s_waitcnt lgkmcnt(1)
	v_mov_b32_e32 v62, v40
	s_waitcnt lgkmcnt(0)
	v_mov_b32_e32 v63, v54
	v_mov_b32_e32 v54, v41
	v_pk_mul_f32 v[40:41], v[24:25], v[54:55]
	v_mov_b32_e32 v54, v42
	v_pk_fma_f32 v[40:41], v[20:21], v[62:63], v[40:41]
	v_mov_b32_e32 v55, v56
	v_pk_fma_f32 v[40:41], v[18:19], v[54:55], v[40:41]
	v_mov_b32_e32 v56, v43
	v_pk_fma_f32 v[40:41], v[14:15], v[56:57], v[40:41]
	s_nop 0
	v_add_f32_e32 v40, v51, v40
	v_add_f32_e32 v53, v40, v41
	ds_read_b128 v[40:43], v52 offset:1440
	ds_read_b128 v[54:57], v52 offset:1456
	s_waitcnt lgkmcnt(1)
	v_mov_b32_e32 v62, v40
	s_waitcnt lgkmcnt(0)
; #define LAS __attribute__((address_space(3)))
; __device__ __forceinline__ void gla_gates(CP P, const bf16_t* PQ, int m0, int h, LAS unsigned char* lds) {
;     ...
;     for (int i = 0; i < 16; ++i) { const int t = tq * 16 + i; float z = b;
; #pragma unroll
;         for (int r4 = 0; r4 < 4; ++r4) { const f32x4 g4 = *(const LAS f32x4*)(gl + t * 32 + dir * 16 + r4 * 4);
;             z += g4[0] * w[r4 * 4] + g4[1] * w[r4 * 4 + 1] + g4[2] * w[r4 * 4 + 2] + g4[3] * w[r4 * 4 + 3]; }
;         c[i] = (fminf(z, 0.f) - __logf(1.0f + __expf(-fabsf(z)))) * (1.0f / 16.0f); }
	v_mov_b32_e32 v63, v54
	v_mov_b32_e32 v54, v41
	v_pk_mul_f32 v[40:41], v[28:29], v[54:55]
	v_mov_b32_e32 v54, v42
	v_pk_fma_f32 v[40:41], v[26:27], v[62:63], v[40:41]
	v_mov_b32_e32 v55, v56
	v_pk_fma_f32 v[40:41], v[22:23], v[54:55], v[40:41]
	v_mov_b32_e32 v56, v43
	v_pk_fma_f32 v[40:41], v[16:17], v[56:57], v[40:41]
	s_nop 0
	v_add_f32_e32 v40, v53, v40
	v_add_f32_e32 v40, v40, v41
	v_min_f32_e32 v59, 0, v40
	v_mul_f32_e64 v40, |v40|, s33
	v_exp_f32_e32 v40, v40
	s_nop 0
	v_add_f32_e32 v40, 1.0, v40
	v_cmp_gt_f32_e32 vcc, s80, v40
	s_nop 1
	v_cndmask_b32_e64 v41, 0, 32, vcc
	v_ldexp_f32 v40, v40, v41
	v_log_f32_e32 v40, v40
	s_nop 0
	v_mul_f32_e32 v41, 0x3f317217, v40
	v_fma_f32 v41, v40, s92, -v41
	v_fmac_f32_e32 v41, 0x3377d1cf, v40
	v_fmac_f32_e32 v41, 0x3f317217, v40
	v_cmp_lt_f32_e64 s[40:41], |v40|, s93
	s_nop 1
	v_cndmask_b32_e64 v40, v40, v41, s[40:41]
	v_cndmask_b32_e32 v41, 0, v231, vcc
	v_sub_f32_e32 v61, v40, v41
	v_pk_add_f32 v[40:41], v[58:59], v[60:61] neg_lo:[0,1] neg_hi:[0,1]
	ds_read_b128 v[54:57], v52 offset:1536
	ds_read_b128 v[58:61], v52 offset:1552
	v_pk_mul_f32 v[40:41], v[40:41], s[78:79] op_sel_hi:[1,0]
	s_waitcnt lgkmcnt(1)
	v_mov_b32_e32 v42, v54
	s_waitcnt lgkmcnt(0)
	v_mov_b32_e32 v43, v58
	v_mov_b32_e32 v58, v55
	v_pk_mul_f32 v[54:55], v[24:25], v[58:59]
	s_nop 0
	v_pk_fma_f32 v[42:43], v[20:21], v[42:43], v[54:55]
	v_mov_b32_e32 v54, v56
	v_mov_b32_e32 v55, v60
	v_pk_fma_f32 v[42:43], v[18:19], v[54:55], v[42:43]
	v_mov_b32_e32 v60, v57
	v_pk_fma_f32 v[42:43], v[14:15], v[60:61], v[42:43]
	ds_read_b128 v[54:57], v52 offset:1568
	ds_read_b128 v[58:61], v52 offset:1584
	v_add_f32_e32 v42, v51, v42
	v_add_f32_e32 v53, v42, v43
	s_waitcnt lgkmcnt(1)
	v_mov_b32_e32 v42, v54
	s_waitcnt lgkmcnt(0)
	v_mov_b32_e32 v43, v58
	v_mov_b32_e32 v58, v55
	v_pk_mul_f32 v[54:55], v[28:29], v[58:59]
	s_nop 0
	v_pk_fma_f32 v[42:43], v[26:27], v[42:43], v[54:55]
	v_mov_b32_e32 v54, v56
	v_mov_b32_e32 v55, v60
	v_pk_fma_f32 v[42:43], v[22:23], v[54:55], v[42:43]
	v_mov_b32_e32 v60, v57
	v_pk_fma_f32 v[42:43], v[16:17], v[60:61], v[42:43]
	ds_read_b128 v[54:57], v52 offset:1664
	ds_read_b128 v[58:61], v52 offset:1680
	v_add_f32_e32 v42, v53, v42
	v_add_f32_e32 v43, v42, v43
	v_min_f32_e32 v42, 0, v43
	v_mul_f32_e64 v43, |v43|, s33
	v_exp_f32_e32 v43, v43
	s_waitcnt lgkmcnt(0)
	v_mov_b32_e32 v65, v58
	v_mov_b32_e32 v58, v55
	v_mov_b32_e32 v64, v54
	v_add_f32_e32 v43, 1.0, v43
	v_cmp_gt_f32_e32 vcc, s80, v43
	v_pk_mul_f32 v[54:55], v[24:25], v[58:59]
	v_mov_b32_e32 v58, v56
	v_cndmask_b32_e64 v53, 0, 32, vcc
	v_ldexp_f32 v43, v43, v53
	v_log_f32_e32 v43, v43
	v_pk_fma_f32 v[54:55], v[20:21], v[64:65], v[54:55]
	v_mov_b32_e32 v59, v60
	v_pk_fma_f32 v[54:55], v[18:19], v[58:59], v[54:55]
	v_mul_f32_e32 v53, 0x3f317217, v43
	v_fma_f32 v53, v43, s92, -v53
	v_fmac_f32_e32 v53, 0x3377d1cf, v43
	v_fmac_f32_e32 v53, 0x3f317217, v43
	v_cmp_lt_f32_e64 s[40:41], |v43|, s93
	v_mov_b32_e32 v60, v57
	v_pk_fma_f32 v[54:55], v[14:15], v[60:61], v[54:55]
	v_cndmask_b32_e64 v43, v43, v53, s[40:41]
	v_cndmask_b32_e32 v53, 0, v231, vcc
	v_sub_f32_e32 v62, v43, v53
	v_add_f32_e32 v43, v51, v54
	v_add_f32_e32 v43, v43, v55
	ds_read_b128 v[54:57], v52 offset:1696
	ds_read_b128 v[58:61], v52 offset:1712
	s_waitcnt lgkmcnt(1)
	v_mov_b32_e32 v64, v54
	s_waitcnt lgkmcnt(0)
	v_mov_b32_e32 v65, v58
	v_mov_b32_e32 v58, v55
	v_pk_mul_f32 v[54:55], v[28:29], v[58:59]
	v_mov_b32_e32 v58, v56
	v_pk_fma_f32 v[54:55], v[26:27], v[64:65], v[54:55]
	v_mov_b32_e32 v59, v60
	v_pk_fma_f32 v[54:55], v[22:23], v[58:59], v[54:55]
	v_mov_b32_e32 v60, v57
	v_pk_fma_f32 v[54:55], v[16:17], v[60:61], v[54:55]
	s_nop 0
	v_add_f32_e32 v43, v43, v54
	v_add_f32_e32 v53, v43, v55
	v_min_f32_e32 v43, 0, v53
	v_mul_f32_e64 v53, |v53|, s33
	v_exp_f32_e32 v53, v53
	s_nop 0
	v_add_f32_e32 v53, 1.0, v53
	v_cmp_gt_f32_e32 vcc, s80, v53
	s_nop 1
	v_cndmask_b32_e64 v54, 0, 32, vcc
	v_ldexp_f32 v53, v53, v54
	v_log_f32_e32 v53, v53
	s_nop 0
	v_mul_f32_e32 v54, 0x3f317217, v53
	v_fma_f32 v54, v53, s92, -v54
	v_fmac_f32_e32 v54, 0x3377d1cf, v53
	v_fmac_f32_e32 v54, 0x3f317217, v53
	v_cmp_lt_f32_e64 s[40:41], |v53|, s93
	s_nop 1
	v_cndmask_b32_e64 v53, v53, v54, s[40:41]
	v_cndmask_b32_e32 v54, 0, v231, vcc
	v_sub_f32_e32 v63, v53, v54
	ds_read_b128 v[54:57], v52 offset:1792
	ds_read_b128 v[58:61], v52 offset:1808
	v_pk_add_f32 v[42:43], v[42:43], v[62:63] neg_lo:[0,1] neg_hi:[0,1]
	s_waitcnt lgkmcnt(1)
; #define LAS __attribute__((address_space(3)))
; __device__ __forceinline__ void gla_gates(CP P, const bf16_t* PQ, int m0, int h, LAS unsigned char* lds) {
;     ...
;     for (int i = 0; i < 16; ++i) { const int t = tq * 16 + i; float z = b;
; #pragma unroll
;         for (int r4 = 0; r4 < 4; ++r4) { const f32x4 g4 = *(const LAS f32x4*)(gl + t * 32 + dir * 16 + r4 * 4);
;             z += g4[0] * w[r4 * 4] + g4[1] * w[r4 * 4 + 1] + g4[2] * w[r4 * 4 + 2] + g4[3] * w[r4 * 4 + 3]; }
;         c[i] = (fminf(z, 0.f) - __logf(1.0f + __expf(-fabsf(z)))) * (1.0f / 16.0f); }
;     if (dir == 0) {
; #pragma unroll
;         for (int i = 1; i < 16; ++i) c[i] += c[i - 1];
;         tot[(dir * 4 + tq) * 64 + d] = c[15]; }
;     else {
; #pragma unroll
;         for (int i = 14; i >= 0; --i) c[i] += c[i + 1];
;         tot[(dir * 4 + tq) * 64 + d] = c[0]; }
	v_mov_b32_e32 v62, v54
	s_waitcnt lgkmcnt(0)
	v_mov_b32_e32 v63, v58
	v_mov_b32_e32 v58, v55
	v_pk_mul_f32 v[54:55], v[24:25], v[58:59]
	v_mov_b32_e32 v58, v56
	v_pk_fma_f32 v[54:55], v[20:21], v[62:63], v[54:55]
	v_mov_b32_e32 v59, v60
	v_pk_fma_f32 v[54:55], v[18:19], v[58:59], v[54:55]
	v_mov_b32_e32 v60, v57
	v_pk_fma_f32 v[54:55], v[14:15], v[60:61], v[54:55]
	v_pk_mul_f32 v[42:43], v[42:43], s[78:79] op_sel_hi:[1,0]
	v_add_f32_e32 v53, v51, v54
	v_add_f32_e32 v53, v53, v55
	ds_read_b128 v[54:57], v52 offset:1824
	ds_read_b128 v[58:61], v52 offset:1840
	s_waitcnt lgkmcnt(1)
	v_mov_b32_e32 v62, v54
	s_waitcnt lgkmcnt(0)
	v_mov_b32_e32 v63, v58
	v_mov_b32_e32 v58, v55
	v_pk_mul_f32 v[54:55], v[28:29], v[58:59]
	v_mov_b32_e32 v58, v56
	v_pk_fma_f32 v[54:55], v[26:27], v[62:63], v[54:55]
	v_mov_b32_e32 v59, v60
	v_pk_fma_f32 v[54:55], v[22:23], v[58:59], v[54:55]
	v_mov_b32_e32 v60, v57
	v_pk_fma_f32 v[54:55], v[16:17], v[60:61], v[54:55]
	s_nop 0
	v_add_f32_e32 v53, v53, v54
	v_add_f32_e32 v53, v53, v55
	v_min_f32_e32 v62, 0, v53
	v_mul_f32_e64 v53, |v53|, s33
	v_exp_f32_e32 v53, v53
	s_nop 0
	v_add_f32_e32 v53, 1.0, v53
	v_cmp_gt_f32_e32 vcc, s80, v53
	s_nop 1
	v_cndmask_b32_e64 v54, 0, 32, vcc
	v_ldexp_f32 v53, v53, v54
	v_log_f32_e32 v53, v53
	s_nop 0
	v_mul_f32_e32 v54, 0x3f317217, v53
	v_fma_f32 v54, v53, s92, -v54
	v_fmac_f32_e32 v54, 0x3377d1cf, v53
	v_fmac_f32_e32 v54, 0x3f317217, v53
	v_cmp_lt_f32_e64 s[40:41], |v53|, s93
	s_nop 1
	v_cndmask_b32_e64 v53, v53, v54, s[40:41]
	v_cndmask_b32_e32 v54, 0, v231, vcc
	v_sub_f32_e32 v64, v53, v54
	ds_read_b128 v[54:57], v52 offset:1920
	ds_read_b128 v[58:61], v52 offset:1936
	s_waitcnt lgkmcnt(1)
	v_mov_b32_e32 v66, v54
	s_waitcnt lgkmcnt(0)
	v_mov_b32_e32 v67, v58
	v_mov_b32_e32 v58, v55
	v_pk_mul_f32 v[24:25], v[24:25], v[58:59]
	s_nop 0
	v_pk_fma_f32 v[20:21], v[20:21], v[66:67], v[24:25]
	v_mov_b32_e32 v24, v56
	v_mov_b32_e32 v25, v60
	v_pk_fma_f32 v[18:19], v[18:19], v[24:25], v[20:21]
	v_mov_b32_e32 v60, v57
	v_pk_fma_f32 v[14:15], v[14:15], v[60:61], v[18:19]
	ds_read_b128 v[18:21], v52 offset:1952
	ds_read_b128 v[52:55], v52 offset:1968
	v_add_f32_e32 v14, v51, v14
	v_add_f32_e32 v24, v14, v15
	s_waitcnt lgkmcnt(1)
	v_mov_b32_e32 v14, v18
	s_waitcnt lgkmcnt(0)
	v_mov_b32_e32 v15, v52
	v_mov_b32_e32 v52, v19
	v_pk_mul_f32 v[18:19], v[28:29], v[52:53]
	s_nop 0
	v_pk_fma_f32 v[14:15], v[26:27], v[14:15], v[18:19]
	v_mov_b32_e32 v18, v20
	v_mov_b32_e32 v19, v54
	v_pk_fma_f32 v[14:15], v[22:23], v[18:19], v[14:15]
	v_mov_b32_e32 v54, v21
	v_pk_fma_f32 v[14:15], v[16:17], v[54:55], v[14:15]
	v_lshlrev_b32_e32 v16, 2, v47
	v_add_f32_e32 v14, v24, v14
	v_add_f32_e32 v14, v14, v15
	v_min_f32_e32 v63, 0, v14
	v_mul_f32_e64 v14, |v14|, s33
	v_exp_f32_e32 v14, v14
	s_nop 0
	v_add_f32_e32 v14, 1.0, v14
	v_cmp_gt_f32_e32 vcc, s80, v14
	s_nop 1
	v_cndmask_b32_e64 v15, 0, 32, vcc
	v_ldexp_f32 v14, v14, v15
	v_log_f32_e32 v14, v14
	s_nop 0
	v_mul_f32_e32 v15, 0x3f317217, v14
	v_fma_f32 v15, v14, s92, -v15
	v_fmac_f32_e32 v15, 0x3377d1cf, v14
	v_fmac_f32_e32 v15, 0x3f317217, v14
	v_cmp_lt_f32_e64 s[40:41], |v14|, s93
	s_nop 1
	v_cndmask_b32_e64 v14, v14, v15, s[40:41]
	v_cndmask_b32_e32 v15, 0, v231, vcc
	v_sub_f32_e32 v65, v14, v15
	v_pk_add_f32 v[14:15], v[62:63], v[64:65] neg_lo:[0,1] neg_hi:[0,1]
	v_cmp_gt_u32_e32 vcc, s12, v49
	s_movk_i32 s12, 0xff
	v_pk_mul_f32 v[14:15], v[14:15], s[78:79] op_sel_hi:[1,0]
	v_cmp_lt_u32_e64 s[40:41], s12, v49
	s_and_saveexec_b64 s[12:13], s[40:41]
	s_xor_b64 s[20:21], exec, s[12:13]
	s_cbranch_execz .LBB0_207
	v_add_f32_e32 v18, v14, v15
	v_add_f32_e32 v19, v43, v18
	v_add_f32_e32 v20, v42, v19
	v_add_f32_e32 v21, v41, v20
	v_add_f32_e32 v22, v40, v21
	v_add_f32_e32 v23, v39, v22
	v_add_f32_e32 v24, v38, v23
	v_add_f32_e32 v25, v37, v24
	v_add_f32_e32 v26, v36, v25
	v_add_f32_e32 v27, v35, v26
	v_add_f32_e32 v28, v34, v27
	v_add_f32_e32 v29, v33, v28
	v_add_f32_e32 v51, v32, v29
	v_add_f32_e32 v52, v31, v51
	v_lshl_add_u32 v14, v50, 2, 0
	v_lshlrev_b32_e32 v17, 8, v48
	v_add_f32_e32 v30, v30, v52
	v_add3_u32 v14, v14, v17, v16
	ds_write_b32 v14, v30 offset:8192

; #define LAS __attribute__((address_space(3)))
; __device__ __forceinline__ u32x4 mk4(unsigned a, unsigned b, unsigned c, unsigned d) { return (u32x4){a, b, c, d}; }
; __device__ __forceinline__ unsigned pack2(float lo, float hi) { const f32x2_t v = {lo, hi}; const bf16x2_t b = __builtin_convertvector(v, bf16x2_t); return __builtin_bit_cast(unsigned, b); }
; __device__ __forceinline__ float bflo(unsigned w) { return __uint_as_float(w << 16); }
; __device__ __forceinline__ float bfhi(unsigned w) { return __uint_as_float(w & 0xffff0000u); }
; __device__ __forceinline__ void gla_gates(CP P, const bf16_t* PQ, int m0, int h, LAS unsigned char* lds) {
;     ...
;     float off = 0.f;
; #pragma unroll
;     for (int q = 0; q < 4; ++q) { const float tv = tot[(dir * 4 + q) * 64 + d]; off += ((dir == 0) ? (q < tq) : (q > tq)) ? tv : 0.f; }
; #pragma unroll
;     for (int i = 0; i < 16; ++i) G[(dir * 64 + tq * 16 + i) * 64 + d] = c[i] + off;
;     lds_barrier();
; __device__ void gla_a_unit(CP P, int unit, LAS unsigned char* lds) {
;     ...
;     { const unsigned rw[4] = {kraw.x, kraw.y, kraw.z, kraw.w}; float ef[8], eb[8];
; #pragma unroll
;         for (int q = 0; q < 2; ++q) { const f32x4 lf = *(const LAS f32x4*)(G + 63 * 64 + d8 + q * 4), cf = *(const LAS f32x4*)(G + t * 64 + d8 + q * 4);
;             const f32x4 lb = *(const LAS f32x4*)(G + 64 * 64 + d8 + q * 4), cb = *(const LAS f32x4*)(G + (64 + t) * 64 + d8 + q * 4);
; #pragma unroll
;             for (int j = 0; j < 4; ++j) { ef[q * 4 + j] = __expf(lf[j] - cf[j]); eb[q * 4 + j] = __expf(lb[j] - cb[j]); } }
;         unsigned of[4], ob[4];
; #pragma unroll
;         for (int i = 0; i < 4; ++i) { const float k0 = bflo(rw[i]), k1 = bfhi(rw[i]); of[i] = pack2(k0 * ef[2 * i], k1 * ef[2 * i + 1]); ob[i] = pack2(k0 * eb[2 * i], k1 * eb[2 * i + 1]); }
;         *(LAS u32x4*)(kA + t * 136 + d8) = mk4(of[0], of[1], of[2], of[3]); *(LAS u32x4*)(kA + t * 136 + 64 + d8) = mk4(ob[0], ob[1], ob[2], ob[3]);
;         *(LAS u32x4*)(Vs + t * 136 + v16) = mk4(vr0.x, vr0.y, vr0.z, vr0.w); *(LAS u32x4*)(Vs + t * 136 + v16 + 8) = mk4(vr1.x, vr1.y, vr1.z, vr1.w); }
;     if (tid < 128) { const int dir = tid >> 6, d = tid & 63; const float last = dir == 0 ? G[63 * 64 + d] : G[64 * 64 + d];
;         GDEC[((size_t)(((b * 4 + h) * 2 + dir) * 128 + c)) * 64 + d] = __expf(last); }
.LBB0_217:
	s_or_b64 exec, exec, s[22:23]
	ds_read_b32 v14, v14 offset:8960
	v_cmp_ne_u32_e64 s[40:41], 0, v48
	v_add_f32_e32 v16, 0, v16
	s_and_b64 s[40:41], vcc, s[40:41]
	v_cndmask_b32_e64 v16, 0, v16, s[40:41]
	v_cmp_eq_u32_e64 s[40:41], 3, v48
	s_or_b64 s[12:13], vcc, s[40:41]
	v_add_f32_e32 v16, v16, v31
	s_waitcnt lgkmcnt(0)
	v_cndmask_b32_e64 v14, v14, 0, s[12:13]
	v_add_f32_e32 v16, v16, v32
	v_add_f32_e32 v14, v16, v14
	v_lshl_add_u32 v16, v47, 2, 0
	v_add_f32_e32 v17, v30, v14
	v_lshlrev_b32_e32 v30, 12, v48
	v_lshlrev_b32_e32 v13, 14, v13
	v_add3_u32 v13, v16, v30, v13
	v_add_f32_e32 v16, v52, v14
	ds_write2st64_b32 v13, v17, v16 offset0:68 offset1:69
	v_add_f32_e32 v16, v51, v14
	v_add_f32_e32 v17, v29, v14
	ds_write2st64_b32 v13, v16, v17 offset0:70 offset1:71
	v_add_f32_e32 v16, v28, v14
	v_add_f32_e32 v17, v27, v14
	ds_write2st64_b32 v13, v16, v17 offset0:72 offset1:73
	v_add_f32_e32 v16, v26, v14
	v_add_f32_e32 v17, v25, v14
	ds_write2st64_b32 v13, v16, v17 offset0:74 offset1:75
	v_add_f32_e32 v16, v24, v14
	v_add_f32_e32 v17, v23, v14
	ds_write2st64_b32 v13, v16, v17 offset0:76 offset1:77
	v_add_f32_e32 v16, v22, v14
	v_add_f32_e32 v17, v21, v14
	ds_write2st64_b32 v13, v16, v17 offset0:78 offset1:79
	v_add_f32_e32 v16, v20, v14
	v_add_f32_e32 v17, v19, v14
	v_lshlrev_b32_e32 v38, 3, v46
	ds_write2st64_b32 v13, v16, v17 offset0:80 offset1:81
	v_add_f32_e32 v16, v18, v14
	v_add_f32_e32 v14, v15, v14
	ds_write2st64_b32 v13, v16, v14 offset0:82 offset1:83
	v_lshlrev_b32_e32 v13, 2, v38
	s_waitcnt lgkmcnt(0)
	s_barrier
	s_waitcnt vmcnt(0)
	v_add_u32_e32 v39, 0, v13
	v_lshl_add_u32 v40, v45, 8, 0
	v_add_u32_e32 v13, v40, v13
	ds_read_b128 v[14:17], v39 offset:33792
	ds_read_b128 v[18:21], v13 offset:33792
	ds_read_b128 v[22:25], v39 offset:33536
	ds_read_b128 v[26:29], v39 offset:33552
	ds_read_b128 v[30:33], v13 offset:17408
	ds_read_b128 v[34:37], v13 offset:17424
	s_waitcnt lgkmcnt(4)
	v_sub_f32_e32 v14, v14, v18
	v_mul_f32_e32 v14, 0x3fb8aa3b, v14
	s_movk_i32 s12, 0x110
	s_waitcnt lgkmcnt(1)
	v_sub_f32_e32 v22, v22, v30
	v_exp_f32_e32 v30, v14
	v_sub_f32_e32 v14, v23, v31
	v_mul_f32_e32 v14, 0x3fb8aa3b, v14
	v_exp_f32_e32 v23, v14
	v_sub_f32_e32 v14, v15, v19
	v_mul_f32_e32 v14, 0x3fb8aa3b, v14
	v_exp_f32_e32 v31, v14
	v_sub_f32_e32 v14, v24, v32
	v_mul_f32_e32 v14, 0x3fb8aa3b, v14
	v_exp_f32_e32 v24, v14
	v_sub_f32_e32 v14, v16, v20
	v_mul_f32_e32 v14, 0x3fb8aa3b, v14
	v_exp_f32_e32 v32, v14
	v_sub_f32_e32 v14, v25, v33
	v_mul_f32_e32 v14, 0x3fb8aa3b, v14
	v_exp_f32_e32 v25, v14
	v_sub_f32_e32 v14, v17, v21
	v_mul_f32_e32 v14, 0x3fb8aa3b, v14
	v_exp_f32_e32 v33, v14
	ds_read_b128 v[14:17], v39 offset:33808
	ds_read_b128 v[18:21], v13 offset:33808
	s_waitcnt lgkmcnt(2)
	v_sub_f32_e32 v13, v26, v34
	v_mul_f32_e32 v13, 0x3fb8aa3b, v13
	v_exp_f32_e32 v26, v13
	v_mul_f32_e32 v22, 0x3fb8aa3b, v22
	s_waitcnt lgkmcnt(0)
	v_sub_f32_e32 v13, v14, v18
	v_mul_f32_e32 v13, 0x3fb8aa3b, v13
	v_exp_f32_e32 v18, v13
	v_sub_f32_e32 v13, v27, v35
	v_mul_f32_e32 v13, 0x3fb8aa3b, v13
	v_exp_f32_e32 v27, v13
	v_sub_f32_e32 v13, v15, v19
	v_mul_f32_e32 v13, 0x3fb8aa3b, v13
	v_exp_f32_e32 v19, v13
	v_sub_f32_e32 v13, v28, v36
	v_mul_f32_e32 v13, 0x3fb8aa3b, v13
	v_exp_f32_e32 v28, v13
	v_sub_f32_e32 v13, v16, v20
	v_exp_f32_e32 v22, v22
	v_mul_f32_e32 v13, 0x3fb8aa3b, v13
	v_exp_f32_e32 v20, v13
	v_sub_f32_e32 v13, v29, v37
	v_mul_f32_e32 v13, 0x3fb8aa3b, v13
	v_exp_f32_e32 v29, v13
	v_sub_f32_e32 v13, v17, v21
	v_lshlrev_b32_e32 v14, 16, v8
	v_and_b32_e32 v15, 0xffff0000, v8
	v_mul_f32_e32 v13, 0x3fb8aa3b, v13
	v_pk_mul_f32 v[16:17], v[22:23], v[14:15]
	v_exp_f32_e32 v21, v13
	v_cvt_pk_bf16_f32 v8, v16, v17
	v_lshlrev_b32_e32 v16, 16, v9
	v_and_b32_e32 v17, 0xffff0000, v9
	v_pk_mul_f32 v[14:15], v[30:31], v[14:15]
	v_pk_mul_f32 v[22:23], v[24:25], v[16:17]
	v_pk_mul_f32 v[16:17], v[32:33], v[16:17]
	v_cvt_pk_bf16_f32 v14, v14, v15
	v_cvt_pk_bf16_f32 v15, v16, v17
	v_lshlrev_b32_e32 v16, 16, v10
	v_and_b32_e32 v17, 0xffff0000, v10
	v_cvt_pk_bf16_f32 v9, v22, v23
	v_pk_mul_f32 v[22:23], v[26:27], v[16:17]
	v_pk_mul_f32 v[16:17], v[18:19], v[16:17]
	v_lshlrev_b32_e32 v18, 16, v11
	v_and_b32_e32 v19, 0xffff0000, v11
	v_cvt_pk_bf16_f32 v10, v22, v23
	v_pk_mul_f32 v[22:23], v[28:29], v[18:19]
	v_pk_mul_f32 v[18:19], v[20:21], v[18:19]
	v_cvt_pk_bf16_f32 v16, v16, v17
	v_cvt_pk_bf16_f32 v17, v18, v19
	v_lshlrev_b32_e32 v13, 4, v45
	v_lshlrev_b32_e32 v18, 1, v38
	v_cvt_pk_bf16_f32 v11, v22, v23
	v_add3_u32 v13, v40, v13, v18
	ds_write_b128 v13, v[8:11] offset:50176
	ds_write_b128 v13, v[14:17] offset:50304
	v_mul_lo_u32 v8, v45, s12
	v_lshlrev_b32_e32 v9, 1, v12
	v_readlane_b32 s12, v254, 38
	s_nop 1
	v_add3_u32 v8, s12, v8, v9
	s_movk_i32 s12, 0x7f
	v_cmp_lt_i32_e32 vcc, s12, v44
	ds_write_b128 v8, v[4:7]
	ds_write_b128 v8, v[0:3] offset:16
	s_and_saveexec_b64 s[20:21], vcc
	s_xor_b64 s[20:21], exec, s[20:21]
	s_lshl_b32 s12, s11, 3
	s_lshl_b32 s13, s10, 1
	s_or_b32 s12, s13, s12
	s_or_saveexec_b64 s[20:21], s[20:21]
	v_and_b32_e32 v3, 63, v44
	v_ashrrev_i32_e32 v1, 6, v44
	v_mov_b32_e32 v2, s12
	s_xor_b64 exec, exec, s[20:21]
	s_cbranch_execz .LBB0_203
	v_lshlrev_b32_e32 v4, 2, v3
	v_lshl_add_u32 v0, v44, 2, 0
	v_add_u32_e32 v2, 0, v4
	v_add_u32_e32 v0, 0x8300, v0
	v_add_u32_e32 v2, 0x8400, v2
	v_cmp_gt_u32_e32 vcc, 64, v44
	s_lshl_b32 s11, s11, 3
	s_lshl_b32 s10, s10, 1
	v_cndmask_b32_e32 v0, v2, v0, vcc
	ds_read_b32 v0, v0
	s_or_b32 s10, s10, s11
	v_add_u32_e32 v2, s10, v1
	v_lshl_or_b32 v6, v2, 7, s18
	v_ashrrev_i32_e32 v7, 31, v6
	s_waitcnt lgkmcnt(0)
	v_mul_f32_e32 v0, 0x3fb8aa3b, v0
	v_exp_f32_e32 v0, v0
	v_lshlrev_b64 v[6:7], 8, v[6:7]
	v_lshl_add_u64 v[6:7], s[30:31], 0, v[6:7]
	v_mov_b32_e32 v5, v184
	v_lshl_add_u64 v[4:5], v[6:7], 0, v[4:5]
	v_mov_b32_e32 v2, s10
	global_store_dword v[4:5], v0, off
	s_branch .LBB0_203
